# layer-1 weight f32->bf16 transpose items (run by idle workgroups in the first Down GEMM's partial round): 16 global loads per loop iteration issued back-to-back with counted vmcnt instead of 8 seriali
# baseline (speedup 1.0000x reference)
; #define LAS __attribute__((address_space(3)))
; __device__ __forceinline__ void transpose_item(const float* W, int K, int N, bf16_t* WT, int k0, int n0, int drow0, LAS float* scr, int lane) {
; #pragma unroll 8
;     for (int i = 0; i < 32; ++i) { const int kk = 2 * i + (lane >> 5); scr[kk * 33 + (lane & 31)] = W[(size_t)(k0 + kk) * N + n0 + (lane & 31)]; }
;     asm volatile("s_waitcnt lgkmcnt(0)" ::: "memory");
.LBB0_440:
	s_lshl_b32 s25, s22, 1
	s_lshl_b32 s24, s5, 1
	v_or_b32_e32 v19, s25, v2
	v_or_b32_e32 v18, s24, v3
	v_add_u32_e32 v0, s4, v19
	v_add_u32_e32 v12, s15, v18
	v_mov_b32_e32 v13, v1
	v_lshlrev_b64 v[16:17], 12, v[0:1]
	v_lshlrev_b64 v[12:13], 12, v[12:13]
	v_lshl_add_u64 v[16:17], v[10:11], 0, v[16:17]
	v_lshl_add_u64 v[12:13], v[10:11], 0, v[12:13]
	global_load_dword v22, v[16:17], off
	global_load_dword v23, v[12:13], off
	v_mad_u64_u32 v[52:53], s[26:27], v19, s50, v[6:7]
	v_mad_u64_u32 v[54:55], s[26:27], v18, s50, v[6:7]
	s_add_i32 s27, s25, 4
	s_add_i32 s26, s24, 4
	v_or_b32_e32 v19, s27, v2
	v_or_b32_e32 v18, s26, v3
	v_mov_b32_e32 v13, v1
	s_add_i32 s22, s22, 16
	s_add_i32 s5, s5, 16
	s_add_i32 s23, s23, -16
	v_add_u32_e32 v0, s4, v19
	v_add_u32_e32 v12, s15, v18
	v_lshlrev_b64 v[16:17], 12, v[0:1]
	v_lshlrev_b64 v[12:13], 12, v[12:13]
	v_lshl_add_u64 v[16:17], v[10:11], 0, v[16:17]
	v_lshl_add_u64 v[12:13], v[10:11], 0, v[12:13]
	global_load_dword v24, v[16:17], off
	global_load_dword v25, v[12:13], off
	v_mad_u64_u32 v[56:57], s[26:27], v19, s50, v[6:7]
	v_mad_u64_u32 v[58:59], s[26:27], v18, s50, v[6:7]
	s_add_i32 s27, s25, 8
	s_add_i32 s26, s24, 8
	v_or_b32_e32 v19, s27, v2
	v_or_b32_e32 v18, s26, v3
	v_mov_b32_e32 v13, v1
	v_add_u32_e32 v0, s4, v19
	v_add_u32_e32 v12, s15, v18
	v_lshlrev_b64 v[16:17], 12, v[0:1]
	v_lshlrev_b64 v[12:13], 12, v[12:13]
	v_lshl_add_u64 v[16:17], v[10:11], 0, v[16:17]
	v_lshl_add_u64 v[12:13], v[10:11], 0, v[12:13]
	global_load_dword v26, v[16:17], off
	global_load_dword v27, v[12:13], off
	v_mad_u64_u32 v[60:61], s[26:27], v19, s50, v[6:7]
	v_mad_u64_u32 v[62:63], s[26:27], v18, s50, v[6:7]
	s_add_i32 s27, s25, 12
	s_add_i32 s26, s24, 12
	v_or_b32_e32 v19, s27, v2
	v_or_b32_e32 v18, s26, v3
	v_mov_b32_e32 v13, v1
	v_add_u32_e32 v0, s4, v19
	v_add_u32_e32 v12, s15, v18
	v_lshlrev_b64 v[16:17], 12, v[0:1]
	v_lshlrev_b64 v[12:13], 12, v[12:13]
	v_lshl_add_u64 v[16:17], v[10:11], 0, v[16:17]
	v_lshl_add_u64 v[12:13], v[10:11], 0, v[12:13]
	global_load_dword v28, v[16:17], off
	global_load_dword v29, v[12:13], off
	v_mad_u64_u32 v[64:65], s[26:27], v19, s50, v[6:7]
	v_mad_u64_u32 v[66:67], s[26:27], v18, s50, v[6:7]
	s_add_i32 s27, s25, 16
	s_add_i32 s26, s24, 16
	v_or_b32_e32 v19, s27, v2
	v_or_b32_e32 v18, s26, v3
	v_mov_b32_e32 v13, v1
	v_add_u32_e32 v0, s4, v19
	v_add_u32_e32 v12, s15, v18
	v_lshlrev_b64 v[16:17], 12, v[0:1]
	v_lshlrev_b64 v[12:13], 12, v[12:13]
	v_lshl_add_u64 v[16:17], v[10:11], 0, v[16:17]
	v_lshl_add_u64 v[12:13], v[10:11], 0, v[12:13]
	global_load_dword v30, v[16:17], off
	global_load_dword v31, v[12:13], off
	v_mad_u64_u32 v[68:69], s[26:27], v19, s50, v[6:7]
	v_mad_u64_u32 v[70:71], s[26:27], v18, s50, v[6:7]
	s_add_i32 s27, s25, 20
	s_add_i32 s26, s24, 20
	v_or_b32_e32 v19, s27, v2
	v_or_b32_e32 v18, s26, v3
	v_mov_b32_e32 v13, v1
	v_add_u32_e32 v0, s4, v19
	v_add_u32_e32 v12, s15, v18
	v_lshlrev_b64 v[16:17], 12, v[0:1]
	v_lshlrev_b64 v[12:13], 12, v[12:13]
	v_lshl_add_u64 v[16:17], v[10:11], 0, v[16:17]
	v_lshl_add_u64 v[12:13], v[10:11], 0, v[12:13]
	global_load_dword v32, v[16:17], off
	global_load_dword v33, v[12:13], off
	v_mad_u64_u32 v[72:73], s[26:27], v19, s50, v[6:7]
	v_mad_u64_u32 v[74:75], s[26:27], v18, s50, v[6:7]
	s_add_i32 s27, s25, 24
	s_add_i32 s26, s24, 24
	v_or_b32_e32 v19, s27, v2
	v_or_b32_e32 v18, s26, v3
	v_mov_b32_e32 v13, v1
	s_add_i32 s25, s25, 28
	s_add_i32 s24, s24, 28
	s_cmp_lg_u32 s23, 0
	v_add_u32_e32 v0, s4, v19
	v_add_u32_e32 v12, s15, v18
	v_lshlrev_b64 v[16:17], 12, v[0:1]
	v_lshlrev_b64 v[12:13], 12, v[12:13]
	v_lshl_add_u64 v[16:17], v[10:11], 0, v[16:17]
	v_lshl_add_u64 v[12:13], v[10:11], 0, v[12:13]
	global_load_dword v34, v[16:17], off
	global_load_dword v35, v[12:13], off
	v_mad_u64_u32 v[76:77], s[26:27], v19, s50, v[6:7]
	v_or_b32_e32 v19, s25, v2
	v_mad_u64_u32 v[78:79], s[26:27], v18, s50, v[6:7]
	v_or_b32_e32 v18, s24, v3
	v_mov_b32_e32 v13, v1
	v_add_u32_e32 v0, s4, v19
	v_add_u32_e32 v12, s15, v18
	v_lshlrev_b64 v[16:17], 12, v[0:1]
	v_lshlrev_b64 v[12:13], 12, v[12:13]
	v_lshl_add_u64 v[16:17], v[10:11], 0, v[16:17]
	v_lshl_add_u64 v[12:13], v[10:11], 0, v[12:13]
	global_load_dword v36, v[16:17], off
	global_load_dword v37, v[12:13], off
	v_mad_u64_u32 v[80:81], s[24:25], v19, s50, v[6:7]
	v_mad_u64_u32 v[82:83], s[24:25], v18, s50, v[6:7]
	s_waitcnt vmcnt(15)
	ds_write_b32 v52, v22
	s_waitcnt vmcnt(14)
	ds_write_b32 v54, v23
	s_waitcnt vmcnt(13)
	ds_write_b32 v56, v24
	s_waitcnt vmcnt(12)
	ds_write_b32 v58, v25
	s_waitcnt vmcnt(11)
	ds_write_b32 v60, v26
	s_waitcnt vmcnt(10)
	ds_write_b32 v62, v27
	s_waitcnt vmcnt(9)
	ds_write_b32 v64, v28
	s_waitcnt vmcnt(8)
	ds_write_b32 v66, v29
	s_waitcnt vmcnt(7)
	ds_write_b32 v68, v30
	s_waitcnt vmcnt(6)
	ds_write_b32 v70, v31
	s_waitcnt vmcnt(5)
	ds_write_b32 v72, v32
	s_waitcnt vmcnt(4)
	ds_write_b32 v74, v33
	s_waitcnt vmcnt(3)
	ds_write_b32 v76, v34
	s_waitcnt vmcnt(2)
	ds_write_b32 v78, v35
	s_waitcnt vmcnt(1)
	ds_write_b32 v80, v36
	s_waitcnt vmcnt(0)
	ds_write_b32 v82, v37
	s_cbranch_scc1 .LBB0_440
; #define LAS __attribute__((address_space(3)))
; __device__ __forceinline__ unsigned pk2(float lo, float hi) { return f2bf(lo) | (f2bf(hi) << 16); }
; __device__ __forceinline__ void transpose_item(const float* W, int K, int N, bf16_t* WT, int k0, int n0, int drow0, LAS float* scr, int lane) {
;     ...
;     const int c = lane & 7;
; #pragma unroll
;     for (int j = 0; j < 4; ++j) { const int n = (lane >> 3) + 8 * j; const LAS float* s = scr + (8 * c) * 33 + n;
;         u32x4 o; o.x = pk2(s[0 * 33], s[1 * 33]); o.y = pk2(s[2 * 33], s[3 * 33]); o.z = pk2(s[4 * 33], s[5 * 33]); o.w = pk2(s[6 * 33], s[7 * 33]);
;         *(u32x4*)(WT + (size_t)(drow0 + n) * K + k0 + 8 * c) = o; }
;     asm volatile("s_waitcnt lgkmcnt(0)" ::: "memory");
	s_mov_b32 s5, s31
	s_lshl_b64 s[4:5], s[4:5], 1
	s_add_u32 s4, s7, s4
	s_waitcnt lgkmcnt(0)
	s_addc_u32 s5, s8, s5
	v_lshlrev_b32_e32 v0, 1, v8
	v_lshl_add_u64 v[10:11], s[4:5], 0, v[0:1]
	ds_read_b32 v0, v7
	ds_read_b32 v12, v7 offset:132
	s_mov_b64 s[4:5], 0x22e0000
	v_lshl_add_u64 v[10:11], v[10:11], 0, s[4:5]
	s_mov_b64 s[4:5], 0
	s_waitcnt lgkmcnt(1)
	v_bfe_u32 v13, v0, 16, 1
	v_add3_u32 v0, v0, v13, s44
	s_waitcnt lgkmcnt(0)
	v_bfe_u32 v13, v12, 16, 1
	v_lshrrev_b32_e32 v0, 16, v0
	v_add3_u32 v12, v12, v13, s44
	v_and_or_b32 v16, v12, s49, v0
	ds_read_b32 v0, v7 offset:264
	ds_read_b32 v12, v7 offset:396
	s_waitcnt lgkmcnt(1)
	v_bfe_u32 v13, v0, 16, 1
	v_add3_u32 v0, v0, v13, s44
	s_waitcnt lgkmcnt(0)
	v_bfe_u32 v13, v12, 16, 1
	v_lshrrev_b32_e32 v0, 16, v0
	v_add3_u32 v12, v12, v13, s44
	v_and_or_b32 v17, v12, s49, v0
	ds_read_b32 v0, v7 offset:528
	ds_read_b32 v12, v7 offset:660
	s_waitcnt lgkmcnt(1)
	v_bfe_u32 v13, v0, 16, 1
	v_add3_u32 v0, v0, v13, s44
	s_waitcnt lgkmcnt(0)
	v_bfe_u32 v13, v12, 16, 1
	v_lshrrev_b32_e32 v0, 16, v0
	v_add3_u32 v12, v12, v13, s44
	v_and_or_b32 v18, v12, s49, v0
	ds_read_b32 v0, v7 offset:792
	ds_read_b32 v12, v7 offset:924
	s_waitcnt lgkmcnt(1)
	v_bfe_u32 v13, v0, 16, 1
	v_add3_u32 v0, v0, v13, s44
	s_waitcnt lgkmcnt(0)
	v_bfe_u32 v13, v12, 16, 1
	v_lshrrev_b32_e32 v0, 16, v0
	v_add3_u32 v12, v12, v13, s44
	v_and_or_b32 v19, v12, s49, v0
	v_or_b32_e32 v0, s14, v5
	v_mul_u32_u24_e32 v0, 0xb00, v0
	v_lshlrev_b32_e32 v0, 1, v0
	v_lshl_add_u64 v[12:13], v[10:11], 0, v[0:1]
	flat_store_dwordx4 v[12:13], v[16:19]
	ds_read_b32 v0, v7 offset:32
	ds_read_b32 v12, v7 offset:164
	s_waitcnt lgkmcnt(0)
	v_bfe_u32 v13, v0, 16, 1
	v_add3_u32 v0, v0, v13, s44
	v_bfe_u32 v13, v12, 16, 1
	v_lshrrev_b32_e32 v0, 16, v0
	v_add3_u32 v12, v12, v13, s44
	v_and_or_b32 v16, v12, s49, v0
	ds_read_b32 v0, v7 offset:296
	ds_read_b32 v12, v7 offset:428
	s_waitcnt lgkmcnt(0)
	v_bfe_u32 v13, v0, 16, 1
	v_add3_u32 v0, v0, v13, s44
	v_bfe_u32 v13, v12, 16, 1
	v_lshrrev_b32_e32 v0, 16, v0
	v_add3_u32 v12, v12, v13, s44
	v_and_or_b32 v17, v12, s49, v0
	ds_read_b32 v0, v7 offset:560
	ds_read_b32 v12, v7 offset:692
	s_waitcnt lgkmcnt(0)
	v_bfe_u32 v13, v0, 16, 1
	v_add3_u32 v0, v0, v13, s44
	v_bfe_u32 v13, v12, 16, 1
	v_lshrrev_b32_e32 v0, 16, v0
	v_add3_u32 v12, v12, v13, s44
	v_and_or_b32 v18, v12, s49, v0
	ds_read_b32 v0, v7 offset:824
	ds_read_b32 v12, v7 offset:956
	s_waitcnt lgkmcnt(0)
	v_bfe_u32 v13, v0, 16, 1
	v_add3_u32 v0, v0, v13, s44
	v_bfe_u32 v13, v12, 16, 1
	v_lshrrev_b32_e32 v0, 16, v0
	v_add3_u32 v12, v12, v13, s44
	v_and_or_b32 v19, v12, s49, v0
	v_or_b32_e32 v0, s14, v9
	v_mul_u32_u24_e32 v0, 0xb00, v0
	v_lshlrev_b32_e32 v0, 1, v0
	v_lshl_add_u64 v[12:13], v[10:11], 0, v[0:1]
	flat_store_dwordx4 v[12:13], v[16:19]
	ds_read_b32 v0, v7 offset:64
	ds_read_b32 v12, v7 offset:196
	s_waitcnt lgkmcnt(0)
	v_bfe_u32 v13, v0, 16, 1
	v_add3_u32 v0, v0, v13, s44
	v_bfe_u32 v13, v12, 16, 1
	v_lshrrev_b32_e32 v0, 16, v0
	v_add3_u32 v12, v12, v13, s44
	v_and_or_b32 v16, v12, s49, v0
	ds_read_b32 v0, v7 offset:328
	ds_read_b32 v12, v7 offset:460
	s_waitcnt lgkmcnt(0)
	v_bfe_u32 v13, v0, 16, 1
	v_add3_u32 v0, v0, v13, s44
	v_bfe_u32 v13, v12, 16, 1
	v_lshrrev_b32_e32 v0, 16, v0
	v_add3_u32 v12, v12, v13, s44
	v_and_or_b32 v17, v12, s49, v0
	ds_read_b32 v0, v7 offset:592
	ds_read_b32 v12, v7 offset:724
	s_waitcnt lgkmcnt(0)
	v_bfe_u32 v13, v0, 16, 1
	v_add3_u32 v0, v0, v13, s44
	v_bfe_u32 v13, v12, 16, 1
	v_lshrrev_b32_e32 v0, 16, v0
	v_add3_u32 v12, v12, v13, s44
	v_and_or_b32 v18, v12, s49, v0
	ds_read_b32 v0, v7 offset:856
	ds_read_b32 v12, v7 offset:988
	s_waitcnt lgkmcnt(0)
	v_bfe_u32 v13, v0, 16, 1
	v_add3_u32 v0, v0, v13, s44
	v_bfe_u32 v13, v12, 16, 1
	v_lshrrev_b32_e32 v0, 16, v0
	v_add3_u32 v12, v12, v13, s44
	v_and_or_b32 v19, v12, s49, v0
	v_or_b32_e32 v0, s14, v14
	v_mul_u32_u24_e32 v0, 0xb00, v0
	v_lshlrev_b32_e32 v0, 1, v0
	v_lshl_add_u64 v[12:13], v[10:11], 0, v[0:1]
	flat_store_dwordx4 v[12:13], v[16:19]
	ds_read_b32 v0, v7 offset:96
	ds_read_b32 v12, v7 offset:228
	s_waitcnt lgkmcnt(0)
	v_bfe_u32 v13, v0, 16, 1
	v_add3_u32 v0, v0, v13, s44
	v_bfe_u32 v13, v12, 16, 1
	v_lshrrev_b32_e32 v0, 16, v0
	v_add3_u32 v12, v12, v13, s44
	v_and_or_b32 v16, v12, s49, v0
	ds_read_b32 v0, v7 offset:360
	ds_read_b32 v12, v7 offset:492
	s_waitcnt lgkmcnt(0)
	v_bfe_u32 v13, v0, 16, 1
	v_add3_u32 v0, v0, v13, s44
	v_bfe_u32 v13, v12, 16, 1
	v_lshrrev_b32_e32 v0, 16, v0
	v_add3_u32 v12, v12, v13, s44
	v_and_or_b32 v17, v12, s49, v0
	ds_read_b32 v0, v7 offset:624
	ds_read_b32 v12, v7 offset:756
	s_waitcnt lgkmcnt(0)
	v_bfe_u32 v13, v0, 16, 1
	v_add3_u32 v0, v0, v13, s44
	v_bfe_u32 v13, v12, 16, 1
	v_lshrrev_b32_e32 v0, 16, v0
	v_add3_u32 v12, v12, v13, s44
	v_and_or_b32 v18, v12, s49, v0
	ds_read_b32 v0, v7 offset:888
	ds_read_b32 v12, v7 offset:1020
	s_waitcnt lgkmcnt(0)
	v_bfe_u32 v13, v0, 16, 1
	v_add3_u32 v0, v0, v13, s44
	v_bfe_u32 v13, v12, 16, 1
	v_lshrrev_b32_e32 v0, 16, v0
	v_add3_u32 v12, v12, v13, s44
	v_and_or_b32 v19, v12, s49, v0
	v_or_b32_e32 v0, s14, v15
	v_mul_u32_u24_e32 v0, 0xb00, v0
	v_lshlrev_b32_e32 v0, 1, v0
	v_lshl_add_u64 v[10:11], v[10:11], 0, v[0:1]
	flat_store_dwordx4 v[10:11], v[16:19]
	s_waitcnt lgkmcnt(0)

; #define LAS __attribute__((address_space(3)))
; __device__ __forceinline__ void transpose_item(const float* W, int K, int N, bf16_t* WT, int k0, int n0, int drow0, LAS float* scr, int lane) {
; #pragma unroll 8
;     for (int i = 0; i < 32; ++i) { const int kk = 2 * i + (lane >> 5); scr[kk * 33 + (lane & 31)] = W[(size_t)(k0 + kk) * N + n0 + (lane & 31)]; }
;     asm volatile("s_waitcnt lgkmcnt(0)" ::: "memory");
.LBB0_444:
	s_lshl_b32 s26, s23, 1
	s_lshl_b32 s25, s22, 1
	v_or_b32_e32 v18, s26, v2
	v_or_b32_e32 v0, s25, v3
	v_add_u32_e32 v12, s4, v18
	v_add_u32_e32 v16, s15, v0
	v_mad_u64_u32 v[12:13], s[36:37], v12, s43, v[10:11]
	v_mad_u64_u32 v[16:17], s[36:37], v16, s43, v[10:11]
	global_load_dword v22, v[12:13], off
	global_load_dword v23, v[16:17], off
	s_add_i32 s30, s26, 4
	v_mad_u64_u32 v[52:53], s[36:37], v18, s50, v[6:7]
	s_add_i32 s27, s25, 4
	v_or_b32_e32 v18, s30, v2
	v_mad_u64_u32 v[54:55], s[36:37], v0, s50, v[6:7]
	v_or_b32_e32 v0, s27, v3
	s_add_i32 s30, s26, 8
	s_add_i32 s27, s25, 8
	s_add_i32 s23, s23, 16
	s_add_i32 s22, s22, 16
	s_add_i32 s24, s24, -16
	v_add_u32_e32 v12, s4, v18
	v_add_u32_e32 v16, s15, v0
	v_mad_u64_u32 v[12:13], s[36:37], v12, s43, v[10:11]
	v_mad_u64_u32 v[16:17], s[36:37], v16, s43, v[10:11]
	global_load_dword v24, v[12:13], off
	global_load_dword v25, v[16:17], off
	v_mad_u64_u32 v[56:57], s[36:37], v18, s50, v[6:7]
	v_or_b32_e32 v18, s30, v2
	v_mad_u64_u32 v[58:59], s[36:37], v0, s50, v[6:7]
	v_or_b32_e32 v0, s27, v3
	s_add_i32 s30, s26, 12
	s_add_i32 s27, s25, 12
	v_add_u32_e32 v12, s4, v18
	v_add_u32_e32 v16, s15, v0
	v_mad_u64_u32 v[12:13], s[36:37], v12, s43, v[10:11]
	v_mad_u64_u32 v[16:17], s[36:37], v16, s43, v[10:11]
	global_load_dword v26, v[12:13], off
	global_load_dword v27, v[16:17], off
	v_mad_u64_u32 v[60:61], s[36:37], v18, s50, v[6:7]
	v_or_b32_e32 v18, s30, v2
	v_mad_u64_u32 v[62:63], s[36:37], v0, s50, v[6:7]
	v_or_b32_e32 v0, s27, v3
	s_add_i32 s30, s26, 16
	s_add_i32 s27, s25, 16
	v_add_u32_e32 v12, s4, v18
	v_add_u32_e32 v16, s15, v0
	v_mad_u64_u32 v[12:13], s[36:37], v12, s43, v[10:11]
	v_mad_u64_u32 v[16:17], s[36:37], v16, s43, v[10:11]
	global_load_dword v28, v[12:13], off
	global_load_dword v29, v[16:17], off
	v_mad_u64_u32 v[64:65], s[36:37], v18, s50, v[6:7]
	v_or_b32_e32 v18, s30, v2
	v_mad_u64_u32 v[66:67], s[36:37], v0, s50, v[6:7]
	v_or_b32_e32 v0, s27, v3
	s_add_i32 s30, s26, 20
	s_add_i32 s27, s25, 20
	v_add_u32_e32 v12, s4, v18
	v_add_u32_e32 v16, s15, v0
	v_mad_u64_u32 v[12:13], s[36:37], v12, s43, v[10:11]
	v_mad_u64_u32 v[16:17], s[36:37], v16, s43, v[10:11]
	global_load_dword v30, v[12:13], off
	global_load_dword v31, v[16:17], off
	v_mad_u64_u32 v[68:69], s[36:37], v18, s50, v[6:7]
	v_or_b32_e32 v18, s30, v2
	v_mad_u64_u32 v[70:71], s[36:37], v0, s50, v[6:7]
	v_or_b32_e32 v0, s27, v3
	s_add_i32 s30, s26, 24
	s_add_i32 s27, s25, 24
	s_add_i32 s26, s26, 28
	s_add_i32 s25, s25, 28
	s_cmp_lg_u32 s24, 0
	v_add_u32_e32 v12, s4, v18
	v_add_u32_e32 v16, s15, v0
	v_mad_u64_u32 v[12:13], s[36:37], v12, s43, v[10:11]
	v_mad_u64_u32 v[16:17], s[36:37], v16, s43, v[10:11]
	global_load_dword v32, v[12:13], off
	global_load_dword v33, v[16:17], off
	v_mad_u64_u32 v[72:73], s[36:37], v18, s50, v[6:7]
	v_or_b32_e32 v18, s30, v2
	v_mad_u64_u32 v[74:75], s[36:37], v0, s50, v[6:7]
	v_or_b32_e32 v0, s27, v3
	v_add_u32_e32 v12, s4, v18
	v_add_u32_e32 v16, s15, v0
	v_mad_u64_u32 v[12:13], s[36:37], v12, s43, v[10:11]
	v_mad_u64_u32 v[16:17], s[36:37], v16, s43, v[10:11]
	global_load_dword v34, v[12:13], off
	global_load_dword v35, v[16:17], off
	v_mad_u64_u32 v[76:77], s[36:37], v18, s50, v[6:7]
	v_or_b32_e32 v18, s26, v2
	v_mad_u64_u32 v[78:79], s[36:37], v0, s50, v[6:7]
	v_or_b32_e32 v0, s25, v3
	v_add_u32_e32 v12, s4, v18
	v_add_u32_e32 v16, s15, v0
	v_mad_u64_u32 v[12:13], s[26:27], v12, s43, v[10:11]
	v_mad_u64_u32 v[16:17], s[26:27], v16, s43, v[10:11]
	global_load_dword v36, v[12:13], off
	global_load_dword v37, v[16:17], off
	v_mad_u64_u32 v[80:81], s[26:27], v18, s50, v[6:7]
	v_mad_u64_u32 v[82:83], s[26:27], v0, s50, v[6:7]
	s_waitcnt vmcnt(15)
	ds_write_b32 v52, v22
	s_waitcnt vmcnt(14)
	ds_write_b32 v54, v23
	s_waitcnt vmcnt(13)
	ds_write_b32 v56, v24
	s_waitcnt vmcnt(12)
	ds_write_b32 v58, v25
	s_waitcnt vmcnt(11)
	ds_write_b32 v60, v26
	s_waitcnt vmcnt(10)
	ds_write_b32 v62, v27
	s_waitcnt vmcnt(9)
	ds_write_b32 v64, v28
	s_waitcnt vmcnt(8)
	ds_write_b32 v66, v29
	s_waitcnt vmcnt(7)
	ds_write_b32 v68, v30
	s_waitcnt vmcnt(6)
	ds_write_b32 v70, v31
	s_waitcnt vmcnt(5)
	ds_write_b32 v72, v32
	s_waitcnt vmcnt(4)
	ds_write_b32 v74, v33
	s_waitcnt vmcnt(3)
	ds_write_b32 v76, v34
	s_waitcnt vmcnt(2)
	ds_write_b32 v78, v35
	s_waitcnt vmcnt(1)
	ds_write_b32 v80, v36
	s_waitcnt vmcnt(0)
	ds_write_b32 v82, v37
	s_cbranch_scc1 .LBB0_444
; #define LAS __attribute__((address_space(3)))
; __device__ __forceinline__ unsigned pk2(float lo, float hi) { return f2bf(lo) | (f2bf(hi) << 16); }
; __device__ __forceinline__ void transpose_item(const float* W, int K, int N, bf16_t* WT, int k0, int n0, int drow0, LAS float* scr, int lane) {
;     ...
;     const int c = lane & 7;
; #pragma unroll
;     for (int j = 0; j < 4; ++j) { const int n = (lane >> 3) + 8 * j; const LAS float* s = scr + (8 * c) * 33 + n;
;         u32x4 o; o.x = pk2(s[0 * 33], s[1 * 33]); o.y = pk2(s[2 * 33], s[3 * 33]); o.z = pk2(s[4 * 33], s[5 * 33]); o.w = pk2(s[6 * 33], s[7 * 33]);
;         *(u32x4*)(WT + (size_t)(drow0 + n) * K + k0 + 8 * c) = o; }
;     asm volatile("s_waitcnt lgkmcnt(0)" ::: "memory");
; }
; template <bool GU> __device__ __forceinline__ void transpose_matrix_item(const float* W, int K, int N, bf16_t* WT, int item, LAS float* scr, int lane) {
;     const int nblk = N / 32, kb = item / nblk, nb = item % nblk, n0 = 32 * nb;
;     int drow0 = n0;
;     if (GU) { const int isu = n0 >= DFF ? 1 : 0, ff0 = n0 - isu * DFF; drow0 = 256 * (ff0 >> 7) + 128 * isu + (ff0 & 127); }
;     transpose_item(W, K, N, WT, 64 * kb, n0, drow0, scr, lane);
	s_and_b32 s14, 0xffff, s14
	s_and_b32 s5, 0xffff, s5
	s_cmpk_gt_u32 s5, 0x57
	s_cselect_b32 s5, 0xfffff500, 0
	s_cselect_b32 s15, 0x80, 0
	s_add_i32 s5, s5, s14
	s_lshl_b32 s5, s5, 1
	s_and_b32 s14, s14, 0x60
	s_and_b32 s5, s5, 0xffffff00
	s_or_b32 s14, s14, s15
	s_and_b32 s4, 0xffff, s4
	s_or_b32 s5, s14, s5
	s_lshl_b32 s4, s4, 1
	s_add_u32 s14, s7, s4
	s_waitcnt lgkmcnt(0)
	s_addc_u32 s15, s8, 0
	v_lshlrev_b32_e32 v0, 1, v8
	v_lshl_add_u64 v[10:11], s[14:15], 0, v[0:1]
	ds_read_b32 v0, v7
	ds_read_b32 v12, v7 offset:132
	s_mov_b64 s[14:15], 0x17e0000
	v_lshl_add_u64 v[10:11], v[10:11], 0, s[14:15]
	s_waitcnt lgkmcnt(0)
	v_bfe_u32 v13, v0, 16, 1
	v_add3_u32 v0, v0, v13, s44
	v_bfe_u32 v13, v12, 16, 1
	v_lshrrev_b32_e32 v0, 16, v0
	v_add3_u32 v12, v12, v13, s44
	v_and_or_b32 v16, v12, s49, v0
	ds_read_b32 v0, v7 offset:264
	ds_read_b32 v12, v7 offset:396
	s_waitcnt lgkmcnt(1)
	v_bfe_u32 v13, v0, 16, 1
	v_add3_u32 v0, v0, v13, s44
	s_waitcnt lgkmcnt(0)
	v_bfe_u32 v13, v12, 16, 1
	v_lshrrev_b32_e32 v0, 16, v0
	v_add3_u32 v12, v12, v13, s44
	v_and_or_b32 v17, v12, s49, v0
	ds_read_b32 v0, v7 offset:528
	ds_read_b32 v12, v7 offset:660
	s_waitcnt lgkmcnt(1)
	v_bfe_u32 v13, v0, 16, 1
	v_add3_u32 v0, v0, v13, s44
	s_waitcnt lgkmcnt(0)
	v_bfe_u32 v13, v12, 16, 1
	v_lshrrev_b32_e32 v0, 16, v0
	v_add3_u32 v12, v12, v13, s44
	v_and_or_b32 v18, v12, s49, v0
	ds_read_b32 v0, v7 offset:792
	ds_read_b32 v12, v7 offset:924
	s_waitcnt lgkmcnt(1)
	v_bfe_u32 v13, v0, 16, 1
	v_add3_u32 v0, v0, v13, s44
	s_waitcnt lgkmcnt(0)
	v_bfe_u32 v13, v12, 16, 1
	v_lshrrev_b32_e32 v0, 16, v0
	v_add3_u32 v12, v12, v13, s44
	v_and_or_b32 v19, v12, s49, v0
	v_or_b32_e32 v12, s5, v5
	v_ashrrev_i32_e32 v13, 31, v12
	v_lshlrev_b64 v[12:13], 11, v[12:13]
	v_lshl_add_u64 v[12:13], v[10:11], 0, v[12:13]
	flat_store_dwordx4 v[12:13], v[16:19]
	ds_read_b32 v0, v7 offset:32
	ds_read_b32 v12, v7 offset:164
	s_waitcnt lgkmcnt(0)
	v_bfe_u32 v13, v0, 16, 1
	v_add3_u32 v0, v0, v13, s44
	v_bfe_u32 v13, v12, 16, 1
	v_lshrrev_b32_e32 v0, 16, v0
	v_add3_u32 v12, v12, v13, s44
	v_and_or_b32 v16, v12, s49, v0
	ds_read_b32 v0, v7 offset:296
	ds_read_b32 v12, v7 offset:428
	s_waitcnt lgkmcnt(0)
	v_bfe_u32 v13, v0, 16, 1
	v_add3_u32 v0, v0, v13, s44
	v_bfe_u32 v13, v12, 16, 1
	v_lshrrev_b32_e32 v0, 16, v0
	v_add3_u32 v12, v12, v13, s44
	v_and_or_b32 v17, v12, s49, v0
	ds_read_b32 v0, v7 offset:560
	ds_read_b32 v12, v7 offset:692
	s_waitcnt lgkmcnt(0)
	v_bfe_u32 v13, v0, 16, 1
	v_add3_u32 v0, v0, v13, s44
	v_bfe_u32 v13, v12, 16, 1
	v_lshrrev_b32_e32 v0, 16, v0
	v_add3_u32 v12, v12, v13, s44
	v_and_or_b32 v18, v12, s49, v0
	ds_read_b32 v0, v7 offset:824
	ds_read_b32 v12, v7 offset:956
	s_waitcnt lgkmcnt(0)
	v_bfe_u32 v13, v0, 16, 1
	v_add3_u32 v0, v0, v13, s44
	v_bfe_u32 v13, v12, 16, 1
	v_lshrrev_b32_e32 v0, 16, v0
	v_add3_u32 v12, v12, v13, s44
	v_and_or_b32 v19, v12, s49, v0
	v_or_b32_e32 v12, s5, v9
	v_ashrrev_i32_e32 v13, 31, v12
	v_lshlrev_b64 v[12:13], 11, v[12:13]
	v_lshl_add_u64 v[12:13], v[10:11], 0, v[12:13]
	flat_store_dwordx4 v[12:13], v[16:19]
	ds_read_b32 v0, v7 offset:64
	ds_read_b32 v12, v7 offset:196
	s_waitcnt lgkmcnt(0)
	v_bfe_u32 v13, v0, 16, 1
	v_add3_u32 v0, v0, v13, s44
	v_bfe_u32 v13, v12, 16, 1
	v_lshrrev_b32_e32 v0, 16, v0
	v_add3_u32 v12, v12, v13, s44
	v_and_or_b32 v16, v12, s49, v0
	ds_read_b32 v0, v7 offset:328
	ds_read_b32 v12, v7 offset:460
	s_waitcnt lgkmcnt(0)
	v_bfe_u32 v13, v0, 16, 1
	v_add3_u32 v0, v0, v13, s44
	v_bfe_u32 v13, v12, 16, 1
	v_lshrrev_b32_e32 v0, 16, v0
	v_add3_u32 v12, v12, v13, s44
	v_and_or_b32 v17, v12, s49, v0
	ds_read_b32 v0, v7 offset:592
	ds_read_b32 v12, v7 offset:724
	s_waitcnt lgkmcnt(0)
	v_bfe_u32 v13, v0, 16, 1
	v_add3_u32 v0, v0, v13, s44
	v_bfe_u32 v13, v12, 16, 1
	v_lshrrev_b32_e32 v0, 16, v0
	v_add3_u32 v12, v12, v13, s44
	v_and_or_b32 v18, v12, s49, v0
	ds_read_b32 v0, v7 offset:856
	ds_read_b32 v12, v7 offset:988
	s_waitcnt lgkmcnt(0)
	v_bfe_u32 v13, v0, 16, 1
	v_add3_u32 v0, v0, v13, s44
	v_bfe_u32 v13, v12, 16, 1
	v_lshrrev_b32_e32 v0, 16, v0
	v_add3_u32 v12, v12, v13, s44
	v_and_or_b32 v19, v12, s49, v0
	v_or_b32_e32 v12, s5, v14
	v_ashrrev_i32_e32 v13, 31, v12
	v_lshlrev_b64 v[12:13], 11, v[12:13]
	v_lshl_add_u64 v[12:13], v[10:11], 0, v[12:13]
	flat_store_dwordx4 v[12:13], v[16:19]
	ds_read_b32 v0, v7 offset:96
	ds_read_b32 v12, v7 offset:228
	s_waitcnt lgkmcnt(0)
	v_bfe_u32 v13, v0, 16, 1
	v_add3_u32 v0, v0, v13, s44
	v_bfe_u32 v13, v12, 16, 1
	v_lshrrev_b32_e32 v0, 16, v0
	v_add3_u32 v12, v12, v13, s44
	v_and_or_b32 v16, v12, s49, v0
	ds_read_b32 v0, v7 offset:360
	ds_read_b32 v12, v7 offset:492
	s_waitcnt lgkmcnt(0)
	v_bfe_u32 v13, v0, 16, 1
	v_add3_u32 v0, v0, v13, s44
	v_bfe_u32 v13, v12, 16, 1
	v_lshrrev_b32_e32 v0, 16, v0
	v_add3_u32 v12, v12, v13, s44
	v_and_or_b32 v17, v12, s49, v0
	ds_read_b32 v0, v7 offset:624
	ds_read_b32 v12, v7 offset:756
	s_waitcnt lgkmcnt(0)
	v_bfe_u32 v13, v0, 16, 1
	v_add3_u32 v0, v0, v13, s44
	v_bfe_u32 v13, v12, 16, 1
	v_lshrrev_b32_e32 v0, 16, v0
	v_add3_u32 v12, v12, v13, s44
	v_and_or_b32 v18, v12, s49, v0
	ds_read_b32 v0, v7 offset:888
	ds_read_b32 v12, v7 offset:1020
	s_waitcnt lgkmcnt(0)
	v_bfe_u32 v13, v0, 16, 1
	v_add3_u32 v0, v0, v13, s44
	v_bfe_u32 v13, v12, 16, 1
	v_lshrrev_b32_e32 v0, 16, v0
	v_add3_u32 v12, v12, v13, s44
	v_and_or_b32 v19, v12, s49, v0
	v_or_b32_e32 v12, s5, v15
	v_ashrrev_i32_e32 v13, 31, v12
	v_lshlrev_b64 v[12:13], 11, v[12:13]
	v_lshl_add_u64 v[10:11], v[10:11], 0, v[12:13]
	flat_store_dwordx4 v[10:11], v[16:19]
	s_waitcnt lgkmcnt(0)

; #define LAS __attribute__((address_space(3)))
; __device__ __forceinline__ void transpose_item(const float* W, int K, int N, bf16_t* WT, int k0, int n0, int drow0, LAS float* scr, int lane) {
; #pragma unroll 8
;     for (int i = 0; i < 32; ++i) { const int kk = 2 * i + (lane >> 5); scr[kk * 33 + (lane & 31)] = W[(size_t)(k0 + kk) * N + n0 + (lane & 31)]; }
;     asm volatile("s_waitcnt lgkmcnt(0)" ::: "memory");
.LBB0_449:
	s_lshl_b32 s25, s22, 1
	s_lshl_b32 s24, s5, 1
	v_or_b32_e32 v19, s25, v2
	v_or_b32_e32 v18, s24, v3
	v_add_u32_e32 v0, s14, v19
	v_add_u32_e32 v12, s15, v18
	v_mov_b32_e32 v13, v1
	v_lshlrev_b64 v[16:17], 12, v[0:1]
	v_lshlrev_b64 v[12:13], 12, v[12:13]
	v_lshl_add_u64 v[16:17], v[10:11], 0, v[16:17]
	v_lshl_add_u64 v[12:13], v[10:11], 0, v[12:13]
	global_load_dword v22, v[16:17], off
	global_load_dword v23, v[12:13], off
	v_mad_u64_u32 v[52:53], s[26:27], v19, s50, v[6:7]
	v_mad_u64_u32 v[54:55], s[26:27], v18, s50, v[6:7]
	s_add_i32 s27, s25, 4
	s_add_i32 s26, s24, 4
	v_or_b32_e32 v19, s27, v2
	v_or_b32_e32 v18, s26, v3
	v_mov_b32_e32 v13, v1
	s_add_i32 s22, s22, 16
	s_add_i32 s5, s5, 16
	s_add_i32 s23, s23, -16
	v_add_u32_e32 v0, s14, v19
	v_add_u32_e32 v12, s15, v18
	v_lshlrev_b64 v[16:17], 12, v[0:1]
	v_lshlrev_b64 v[12:13], 12, v[12:13]
	v_lshl_add_u64 v[16:17], v[10:11], 0, v[16:17]
	v_lshl_add_u64 v[12:13], v[10:11], 0, v[12:13]
	global_load_dword v24, v[16:17], off
	global_load_dword v25, v[12:13], off
	v_mad_u64_u32 v[56:57], s[26:27], v19, s50, v[6:7]
	v_mad_u64_u32 v[58:59], s[26:27], v18, s50, v[6:7]
	s_add_i32 s27, s25, 8
	s_add_i32 s26, s24, 8
	v_or_b32_e32 v19, s27, v2
	v_or_b32_e32 v18, s26, v3
	v_mov_b32_e32 v13, v1
	v_add_u32_e32 v0, s14, v19
	v_add_u32_e32 v12, s15, v18
	v_lshlrev_b64 v[16:17], 12, v[0:1]
	v_lshlrev_b64 v[12:13], 12, v[12:13]
	v_lshl_add_u64 v[16:17], v[10:11], 0, v[16:17]
	v_lshl_add_u64 v[12:13], v[10:11], 0, v[12:13]
	global_load_dword v26, v[16:17], off
	global_load_dword v27, v[12:13], off
	v_mad_u64_u32 v[60:61], s[26:27], v19, s50, v[6:7]
	v_mad_u64_u32 v[62:63], s[26:27], v18, s50, v[6:7]
	s_add_i32 s27, s25, 12
	s_add_i32 s26, s24, 12
	v_or_b32_e32 v19, s27, v2
	v_or_b32_e32 v18, s26, v3
	v_mov_b32_e32 v13, v1
	v_add_u32_e32 v0, s14, v19
	v_add_u32_e32 v12, s15, v18
	v_lshlrev_b64 v[16:17], 12, v[0:1]
	v_lshlrev_b64 v[12:13], 12, v[12:13]
	v_lshl_add_u64 v[16:17], v[10:11], 0, v[16:17]
	v_lshl_add_u64 v[12:13], v[10:11], 0, v[12:13]
	global_load_dword v28, v[16:17], off
	global_load_dword v29, v[12:13], off
	v_mad_u64_u32 v[64:65], s[26:27], v19, s50, v[6:7]
	v_mad_u64_u32 v[66:67], s[26:27], v18, s50, v[6:7]
	s_add_i32 s27, s25, 16
	s_add_i32 s26, s24, 16
	v_or_b32_e32 v19, s27, v2
	v_or_b32_e32 v18, s26, v3
	v_mov_b32_e32 v13, v1
	v_add_u32_e32 v0, s14, v19
	v_add_u32_e32 v12, s15, v18
	v_lshlrev_b64 v[16:17], 12, v[0:1]
	v_lshlrev_b64 v[12:13], 12, v[12:13]
	v_lshl_add_u64 v[16:17], v[10:11], 0, v[16:17]
	v_lshl_add_u64 v[12:13], v[10:11], 0, v[12:13]
	global_load_dword v30, v[16:17], off
	global_load_dword v31, v[12:13], off
	v_mad_u64_u32 v[68:69], s[26:27], v19, s50, v[6:7]
	v_mad_u64_u32 v[70:71], s[26:27], v18, s50, v[6:7]
	s_add_i32 s27, s25, 20
	s_add_i32 s26, s24, 20
	v_or_b32_e32 v19, s27, v2
	v_or_b32_e32 v18, s26, v3
	v_mov_b32_e32 v13, v1
	v_add_u32_e32 v0, s14, v19
	v_add_u32_e32 v12, s15, v18
	v_lshlrev_b64 v[16:17], 12, v[0:1]
	v_lshlrev_b64 v[12:13], 12, v[12:13]
	v_lshl_add_u64 v[16:17], v[10:11], 0, v[16:17]
	v_lshl_add_u64 v[12:13], v[10:11], 0, v[12:13]
	global_load_dword v32, v[16:17], off
	global_load_dword v33, v[12:13], off
	v_mad_u64_u32 v[72:73], s[26:27], v19, s50, v[6:7]
	v_mad_u64_u32 v[74:75], s[26:27], v18, s50, v[6:7]
	s_add_i32 s27, s25, 24
	s_add_i32 s26, s24, 24
	v_or_b32_e32 v19, s27, v2
	v_or_b32_e32 v18, s26, v3
	v_mov_b32_e32 v13, v1
	s_add_i32 s25, s25, 28
	s_add_i32 s24, s24, 28
	s_cmp_lg_u32 s23, 0
	v_add_u32_e32 v0, s14, v19
	v_add_u32_e32 v12, s15, v18
	v_lshlrev_b64 v[16:17], 12, v[0:1]
	v_lshlrev_b64 v[12:13], 12, v[12:13]
	v_lshl_add_u64 v[16:17], v[10:11], 0, v[16:17]
	v_lshl_add_u64 v[12:13], v[10:11], 0, v[12:13]
	global_load_dword v34, v[16:17], off
	global_load_dword v35, v[12:13], off
	v_mad_u64_u32 v[76:77], s[26:27], v19, s50, v[6:7]
	v_or_b32_e32 v19, s25, v2
	v_mad_u64_u32 v[78:79], s[26:27], v18, s50, v[6:7]
	v_or_b32_e32 v18, s24, v3
	v_mov_b32_e32 v13, v1
	v_add_u32_e32 v0, s14, v19
	v_add_u32_e32 v12, s15, v18
	v_lshlrev_b64 v[16:17], 12, v[0:1]
	v_lshlrev_b64 v[12:13], 12, v[12:13]
	v_lshl_add_u64 v[16:17], v[10:11], 0, v[16:17]
	v_lshl_add_u64 v[12:13], v[10:11], 0, v[12:13]
	global_load_dword v36, v[16:17], off
	global_load_dword v37, v[12:13], off
	v_mad_u64_u32 v[80:81], s[24:25], v19, s50, v[6:7]
	v_mad_u64_u32 v[82:83], s[24:25], v18, s50, v[6:7]
	s_waitcnt vmcnt(15)
	ds_write_b32 v52, v22
	s_waitcnt vmcnt(14)
	ds_write_b32 v54, v23
	s_waitcnt vmcnt(13)
	ds_write_b32 v56, v24
	s_waitcnt vmcnt(12)
	ds_write_b32 v58, v25
	s_waitcnt vmcnt(11)
	ds_write_b32 v60, v26
	s_waitcnt vmcnt(10)
	ds_write_b32 v62, v27
	s_waitcnt vmcnt(9)
	ds_write_b32 v64, v28
	s_waitcnt vmcnt(8)
	ds_write_b32 v66, v29
	s_waitcnt vmcnt(7)
	ds_write_b32 v68, v30
	s_waitcnt vmcnt(6)
	ds_write_b32 v70, v31
	s_waitcnt vmcnt(5)
	ds_write_b32 v72, v32
	s_waitcnt vmcnt(4)
	ds_write_b32 v74, v33
	s_waitcnt vmcnt(3)
	ds_write_b32 v76, v34
	s_waitcnt vmcnt(2)
	ds_write_b32 v78, v35
	s_waitcnt vmcnt(1)
	ds_write_b32 v80, v36
	s_waitcnt vmcnt(0)
	ds_write_b32 v82, v37
	s_cbranch_scc1 .LBB0_449
; #define LAS __attribute__((address_space(3)))
; __device__ __forceinline__ unsigned pk2(float lo, float hi) { return f2bf(lo) | (f2bf(hi) << 16); }
; __device__ __forceinline__ void transpose_item(const float* W, int K, int N, bf16_t* WT, int k0, int n0, int drow0, LAS float* scr, int lane) {
;     ...
;     const int c = lane & 7;
; #pragma unroll
;     for (int j = 0; j < 4; ++j) { const int n = (lane >> 3) + 8 * j; const LAS float* s = scr + (8 * c) * 33 + n;
;         u32x4 o; o.x = pk2(s[0 * 33], s[1 * 33]); o.y = pk2(s[2 * 33], s[3 * 33]); o.z = pk2(s[4 * 33], s[5 * 33]); o.w = pk2(s[6 * 33], s[7 * 33]);
;         *(u32x4*)(WT + (size_t)(drow0 + n) * K + k0 + 8 * c) = o; }
;     asm volatile("s_waitcnt lgkmcnt(0)" ::: "memory");
	s_lshl_b32 s5, s14, 1
	s_add_u32 s14, s7, s5
	s_waitcnt lgkmcnt(0)
	s_addc_u32 s15, s8, 0
	v_lshlrev_b32_e32 v0, 1, v8
	v_lshl_add_u64 v[10:11], s[14:15], 0, v[0:1]
	ds_read_b32 v0, v7
	ds_read_b32 v12, v7 offset:132
	s_mov_b64 s[14:15], 0x15e0000
	v_lshl_add_u64 v[10:11], v[10:11], 0, s[14:15]
	s_waitcnt lgkmcnt(0)
	v_bfe_u32 v13, v0, 16, 1
	v_add3_u32 v0, v0, v13, s44
	v_bfe_u32 v13, v12, 16, 1
	v_lshrrev_b32_e32 v0, 16, v0
	v_add3_u32 v12, v12, v13, s44
	v_and_or_b32 v16, v12, s49, v0
	ds_read_b32 v0, v7 offset:264
	ds_read_b32 v12, v7 offset:396
	s_waitcnt lgkmcnt(1)
	v_bfe_u32 v13, v0, 16, 1
	v_add3_u32 v0, v0, v13, s44
	s_waitcnt lgkmcnt(0)
	v_bfe_u32 v13, v12, 16, 1
	v_lshrrev_b32_e32 v0, 16, v0
	v_add3_u32 v12, v12, v13, s44
	v_and_or_b32 v17, v12, s49, v0
	ds_read_b32 v0, v7 offset:528
	ds_read_b32 v12, v7 offset:660
	s_waitcnt lgkmcnt(1)
	v_bfe_u32 v13, v0, 16, 1
	v_add3_u32 v0, v0, v13, s44
	s_waitcnt lgkmcnt(0)
	v_bfe_u32 v13, v12, 16, 1
	v_lshrrev_b32_e32 v0, 16, v0
	v_add3_u32 v12, v12, v13, s44
	v_and_or_b32 v18, v12, s49, v0
	ds_read_b32 v0, v7 offset:792
	ds_read_b32 v12, v7 offset:924
	s_waitcnt lgkmcnt(1)
	v_bfe_u32 v13, v0, 16, 1
	v_add3_u32 v0, v0, v13, s44
	s_waitcnt lgkmcnt(0)
	v_bfe_u32 v13, v12, 16, 1
	v_lshrrev_b32_e32 v0, 16, v0
	v_add3_u32 v12, v12, v13, s44
	v_and_or_b32 v19, v12, s49, v0
	v_or_b32_e32 v0, s4, v5
	v_lshlrev_b32_e32 v0, 11, v0
	v_lshl_add_u64 v[12:13], v[10:11], 0, v[0:1]
	flat_store_dwordx4 v[12:13], v[16:19]
	ds_read_b32 v0, v7 offset:32
	ds_read_b32 v12, v7 offset:164
	s_waitcnt lgkmcnt(0)
	v_bfe_u32 v13, v0, 16, 1
	v_add3_u32 v0, v0, v13, s44
	v_bfe_u32 v13, v12, 16, 1
	v_lshrrev_b32_e32 v0, 16, v0
	v_add3_u32 v12, v12, v13, s44
	v_and_or_b32 v16, v12, s49, v0
	ds_read_b32 v0, v7 offset:296
	ds_read_b32 v12, v7 offset:428
	s_waitcnt lgkmcnt(0)
	v_bfe_u32 v13, v0, 16, 1
	v_add3_u32 v0, v0, v13, s44
	v_bfe_u32 v13, v12, 16, 1
	v_lshrrev_b32_e32 v0, 16, v0
	v_add3_u32 v12, v12, v13, s44
	v_and_or_b32 v17, v12, s49, v0
	ds_read_b32 v0, v7 offset:560
	ds_read_b32 v12, v7 offset:692
	s_waitcnt lgkmcnt(0)
	v_bfe_u32 v13, v0, 16, 1
	v_add3_u32 v0, v0, v13, s44
	v_bfe_u32 v13, v12, 16, 1
	v_lshrrev_b32_e32 v0, 16, v0
	v_add3_u32 v12, v12, v13, s44
	v_and_or_b32 v18, v12, s49, v0
	ds_read_b32 v0, v7 offset:824
	ds_read_b32 v12, v7 offset:956
	s_waitcnt lgkmcnt(0)
	v_bfe_u32 v13, v0, 16, 1
	v_add3_u32 v0, v0, v13, s44
	v_bfe_u32 v13, v12, 16, 1
	v_lshrrev_b32_e32 v0, 16, v0
	v_add3_u32 v12, v12, v13, s44
	v_and_or_b32 v19, v12, s49, v0
	v_or_b32_e32 v0, s4, v9
	v_lshlrev_b32_e32 v0, 11, v0
	v_lshl_add_u64 v[12:13], v[10:11], 0, v[0:1]
	flat_store_dwordx4 v[12:13], v[16:19]
	ds_read_b32 v0, v7 offset:64
	ds_read_b32 v12, v7 offset:196
	s_waitcnt lgkmcnt(0)
	v_bfe_u32 v13, v0, 16, 1
	v_add3_u32 v0, v0, v13, s44
	v_bfe_u32 v13, v12, 16, 1
	v_lshrrev_b32_e32 v0, 16, v0
	v_add3_u32 v12, v12, v13, s44
	v_and_or_b32 v16, v12, s49, v0
	ds_read_b32 v0, v7 offset:328
	ds_read_b32 v12, v7 offset:460
	s_waitcnt lgkmcnt(0)
	v_bfe_u32 v13, v0, 16, 1
	v_add3_u32 v0, v0, v13, s44
	v_bfe_u32 v13, v12, 16, 1
	v_lshrrev_b32_e32 v0, 16, v0
	v_add3_u32 v12, v12, v13, s44
	v_and_or_b32 v17, v12, s49, v0
	ds_read_b32 v0, v7 offset:592
	ds_read_b32 v12, v7 offset:724
	s_waitcnt lgkmcnt(0)
	v_bfe_u32 v13, v0, 16, 1
	v_add3_u32 v0, v0, v13, s44
	v_bfe_u32 v13, v12, 16, 1
	v_lshrrev_b32_e32 v0, 16, v0
	v_add3_u32 v12, v12, v13, s44
	v_and_or_b32 v18, v12, s49, v0
	ds_read_b32 v0, v7 offset:856
	ds_read_b32 v12, v7 offset:988
	s_waitcnt lgkmcnt(0)
	v_bfe_u32 v13, v0, 16, 1
	v_add3_u32 v0, v0, v13, s44
	v_bfe_u32 v13, v12, 16, 1
	v_lshrrev_b32_e32 v0, 16, v0
	v_add3_u32 v12, v12, v13, s44
	v_and_or_b32 v19, v12, s49, v0
	v_or_b32_e32 v0, s4, v14
	v_lshlrev_b32_e32 v0, 11, v0
	v_lshl_add_u64 v[12:13], v[10:11], 0, v[0:1]
	flat_store_dwordx4 v[12:13], v[16:19]
	ds_read_b32 v0, v7 offset:96
	ds_read_b32 v12, v7 offset:228
	s_waitcnt lgkmcnt(0)
	v_bfe_u32 v13, v0, 16, 1
	v_add3_u32 v0, v0, v13, s44
	v_bfe_u32 v13, v12, 16, 1
	v_lshrrev_b32_e32 v0, 16, v0
	v_add3_u32 v12, v12, v13, s44
	v_and_or_b32 v16, v12, s49, v0
	ds_read_b32 v0, v7 offset:360
	ds_read_b32 v12, v7 offset:492
	s_waitcnt lgkmcnt(0)
	v_bfe_u32 v13, v0, 16, 1
	v_add3_u32 v0, v0, v13, s44
	v_bfe_u32 v13, v12, 16, 1
	v_lshrrev_b32_e32 v0, 16, v0
	v_add3_u32 v12, v12, v13, s44
	v_and_or_b32 v17, v12, s49, v0
	ds_read_b32 v0, v7 offset:624
	ds_read_b32 v12, v7 offset:756
	s_waitcnt lgkmcnt(0)
	v_bfe_u32 v13, v0, 16, 1
	v_add3_u32 v0, v0, v13, s44
	v_bfe_u32 v13, v12, 16, 1
	v_lshrrev_b32_e32 v0, 16, v0
	v_add3_u32 v12, v12, v13, s44
	v_and_or_b32 v18, v12, s49, v0
	ds_read_b32 v0, v7 offset:888
	ds_read_b32 v12, v7 offset:1020
	s_waitcnt lgkmcnt(0)
	v_bfe_u32 v13, v0, 16, 1
	v_add3_u32 v0, v0, v13, s44
	v_bfe_u32 v13, v12, 16, 1
	v_lshrrev_b32_e32 v0, 16, v0
	v_add3_u32 v12, v12, v13, s44
	v_and_or_b32 v19, v12, s49, v0
	v_or_b32_e32 v0, s4, v15
	v_lshlrev_b32_e32 v0, 11, v0
	v_lshl_add_u64 v[10:11], v[10:11], 0, v[0:1]
	flat_store_dwordx4 v[10:11], v[16:19]
	s_waitcnt lgkmcnt(0)

; #define LAS __attribute__((address_space(3)))
; __device__ __forceinline__ void transpose_item(const float* W, int K, int N, bf16_t* WT, int k0, int n0, int drow0, LAS float* scr, int lane) {
; #pragma unroll 8
;     for (int i = 0; i < 32; ++i) { const int kk = 2 * i + (lane >> 5); scr[kk * 33 + (lane & 31)] = W[(size_t)(k0 + kk) * N + n0 + (lane & 31)]; }
;     asm volatile("s_waitcnt lgkmcnt(0)" ::: "memory");
.LBB0_454:
	s_lshl_b32 s23, s4, 1
	s_lshl_b32 s22, s14, 1
	v_or_b32_e32 v19, s23, v2
	v_or_b32_e32 v18, s22, v3
	v_add_u32_e32 v0, s1, v19
	v_add_u32_e32 v12, s5, v18
	v_mov_b32_e32 v13, v1
	v_lshlrev_b64 v[16:17], 11, v[0:1]
	v_lshlrev_b64 v[12:13], 11, v[12:13]
	v_lshl_add_u64 v[16:17], v[10:11], 0, v[16:17]
	v_lshl_add_u64 v[12:13], v[10:11], 0, v[12:13]
	global_load_dword v22, v[16:17], off
	global_load_dword v23, v[12:13], off
	v_mad_u64_u32 v[52:53], s[24:25], v19, s50, v[6:7]
	v_mad_u64_u32 v[54:55], s[24:25], v18, s50, v[6:7]
	s_add_i32 s25, s23, 4
	s_add_i32 s24, s22, 4
	v_or_b32_e32 v19, s25, v2
	v_or_b32_e32 v18, s24, v3
	v_mov_b32_e32 v13, v1
	s_add_i32 s4, s4, 16
	s_add_i32 s14, s14, 16
	s_add_i32 s15, s15, -16
	v_add_u32_e32 v0, s1, v19
	v_add_u32_e32 v12, s5, v18
	v_lshlrev_b64 v[16:17], 11, v[0:1]
	v_lshlrev_b64 v[12:13], 11, v[12:13]
	v_lshl_add_u64 v[16:17], v[10:11], 0, v[16:17]
	v_lshl_add_u64 v[12:13], v[10:11], 0, v[12:13]
	global_load_dword v24, v[16:17], off
	global_load_dword v25, v[12:13], off
	v_mad_u64_u32 v[56:57], s[24:25], v19, s50, v[6:7]
	v_mad_u64_u32 v[58:59], s[24:25], v18, s50, v[6:7]
	s_add_i32 s25, s23, 8
	s_add_i32 s24, s22, 8
	v_or_b32_e32 v19, s25, v2
	v_or_b32_e32 v18, s24, v3
	v_mov_b32_e32 v13, v1
	v_add_u32_e32 v0, s1, v19
	v_add_u32_e32 v12, s5, v18
	v_lshlrev_b64 v[16:17], 11, v[0:1]
	v_lshlrev_b64 v[12:13], 11, v[12:13]
	v_lshl_add_u64 v[16:17], v[10:11], 0, v[16:17]
	v_lshl_add_u64 v[12:13], v[10:11], 0, v[12:13]
	global_load_dword v26, v[16:17], off
	global_load_dword v27, v[12:13], off
	v_mad_u64_u32 v[60:61], s[24:25], v19, s50, v[6:7]
	v_mad_u64_u32 v[62:63], s[24:25], v18, s50, v[6:7]
	s_add_i32 s25, s23, 12
	s_add_i32 s24, s22, 12
	v_or_b32_e32 v19, s25, v2
	v_or_b32_e32 v18, s24, v3
	v_mov_b32_e32 v13, v1
	v_add_u32_e32 v0, s1, v19
	v_add_u32_e32 v12, s5, v18
	v_lshlrev_b64 v[16:17], 11, v[0:1]
	v_lshlrev_b64 v[12:13], 11, v[12:13]
	v_lshl_add_u64 v[16:17], v[10:11], 0, v[16:17]
	v_lshl_add_u64 v[12:13], v[10:11], 0, v[12:13]
	global_load_dword v28, v[16:17], off
	global_load_dword v29, v[12:13], off
	v_mad_u64_u32 v[64:65], s[24:25], v19, s50, v[6:7]
	v_mad_u64_u32 v[66:67], s[24:25], v18, s50, v[6:7]
	s_add_i32 s25, s23, 16
	s_add_i32 s24, s22, 16
	v_or_b32_e32 v19, s25, v2
	v_or_b32_e32 v18, s24, v3
	v_mov_b32_e32 v13, v1
	v_add_u32_e32 v0, s1, v19
	v_add_u32_e32 v12, s5, v18
	v_lshlrev_b64 v[16:17], 11, v[0:1]
	v_lshlrev_b64 v[12:13], 11, v[12:13]
	v_lshl_add_u64 v[16:17], v[10:11], 0, v[16:17]
	v_lshl_add_u64 v[12:13], v[10:11], 0, v[12:13]
	global_load_dword v30, v[16:17], off
	global_load_dword v31, v[12:13], off
	v_mad_u64_u32 v[68:69], s[24:25], v19, s50, v[6:7]
	v_mad_u64_u32 v[70:71], s[24:25], v18, s50, v[6:7]
	s_add_i32 s25, s23, 20
	s_add_i32 s24, s22, 20
	v_or_b32_e32 v19, s25, v2
	v_or_b32_e32 v18, s24, v3
	v_mov_b32_e32 v13, v1
	v_add_u32_e32 v0, s1, v19
	v_add_u32_e32 v12, s5, v18
	v_lshlrev_b64 v[16:17], 11, v[0:1]
	v_lshlrev_b64 v[12:13], 11, v[12:13]
	v_lshl_add_u64 v[16:17], v[10:11], 0, v[16:17]
	v_lshl_add_u64 v[12:13], v[10:11], 0, v[12:13]
	global_load_dword v32, v[16:17], off
	global_load_dword v33, v[12:13], off
	v_mad_u64_u32 v[72:73], s[24:25], v19, s50, v[6:7]
	v_mad_u64_u32 v[74:75], s[24:25], v18, s50, v[6:7]
	s_add_i32 s25, s23, 24
	s_add_i32 s24, s22, 24
	v_or_b32_e32 v19, s25, v2
	v_or_b32_e32 v18, s24, v3
	v_mov_b32_e32 v13, v1
	s_add_i32 s23, s23, 28
	s_add_i32 s22, s22, 28
	s_cmp_lg_u32 s15, 0
	v_add_u32_e32 v0, s1, v19
	v_add_u32_e32 v12, s5, v18
	v_lshlrev_b64 v[16:17], 11, v[0:1]
	v_lshlrev_b64 v[12:13], 11, v[12:13]
	v_lshl_add_u64 v[16:17], v[10:11], 0, v[16:17]
	v_lshl_add_u64 v[12:13], v[10:11], 0, v[12:13]
	global_load_dword v34, v[16:17], off
	global_load_dword v35, v[12:13], off
	v_mad_u64_u32 v[76:77], s[24:25], v19, s50, v[6:7]
	v_or_b32_e32 v19, s23, v2
	v_mad_u64_u32 v[78:79], s[24:25], v18, s50, v[6:7]
	v_or_b32_e32 v18, s22, v3
	v_mov_b32_e32 v13, v1
	v_add_u32_e32 v0, s1, v19
	v_add_u32_e32 v12, s5, v18
	v_lshlrev_b64 v[16:17], 11, v[0:1]
	v_lshlrev_b64 v[12:13], 11, v[12:13]
	v_lshl_add_u64 v[16:17], v[10:11], 0, v[16:17]
	v_lshl_add_u64 v[12:13], v[10:11], 0, v[12:13]
	global_load_dword v36, v[16:17], off
	global_load_dword v37, v[12:13], off
	v_mad_u64_u32 v[80:81], s[22:23], v19, s50, v[6:7]
	v_mad_u64_u32 v[82:83], s[22:23], v18, s50, v[6:7]
	s_waitcnt vmcnt(15)
	ds_write_b32 v52, v22
	s_waitcnt vmcnt(14)
	ds_write_b32 v54, v23
	s_waitcnt vmcnt(13)
	ds_write_b32 v56, v24
	s_waitcnt vmcnt(12)
	ds_write_b32 v58, v25
	s_waitcnt vmcnt(11)
	ds_write_b32 v60, v26
	s_waitcnt vmcnt(10)
	ds_write_b32 v62, v27
	s_waitcnt vmcnt(9)
	ds_write_b32 v64, v28
	s_waitcnt vmcnt(8)
	ds_write_b32 v66, v29
	s_waitcnt vmcnt(7)
	ds_write_b32 v68, v30
	s_waitcnt vmcnt(6)
	ds_write_b32 v70, v31
	s_waitcnt vmcnt(5)
	ds_write_b32 v72, v32
	s_waitcnt vmcnt(4)
	ds_write_b32 v74, v33
	s_waitcnt vmcnt(3)
	ds_write_b32 v76, v34
	s_waitcnt vmcnt(2)
	ds_write_b32 v78, v35
	s_waitcnt vmcnt(1)
	ds_write_b32 v80, v36
	s_waitcnt vmcnt(0)
	ds_write_b32 v82, v37
	s_cbranch_scc1 .LBB0_454
; #define LAS __attribute__((address_space(3)))
; __device__ __forceinline__ unsigned pk2(float lo, float hi) { return f2bf(lo) | (f2bf(hi) << 16); }
; __device__ __forceinline__ void transpose_item(const float* W, int K, int N, bf16_t* WT, int k0, int n0, int drow0, LAS float* scr, int lane) {
;     ...
;     const int c = lane & 7;
; #pragma unroll
;     for (int j = 0; j < 4; ++j) { const int n = (lane >> 3) + 8 * j; const LAS float* s = scr + (8 * c) * 33 + n;
;         u32x4 o; o.x = pk2(s[0 * 33], s[1 * 33]); o.y = pk2(s[2 * 33], s[3 * 33]); o.z = pk2(s[4 * 33], s[5 * 33]); o.w = pk2(s[6 * 33], s[7 * 33]);
;         *(u32x4*)(WT + (size_t)(drow0 + n) * K + k0 + 8 * c) = o; }
;     asm volatile("s_waitcnt lgkmcnt(0)" ::: "memory");
	s_lshl_b32 s1, s1, 1
	s_add_u32 s4, s7, s1
	s_waitcnt lgkmcnt(0)
	s_addc_u32 s5, s8, 0
	v_lshlrev_b32_e32 v0, 1, v8
	v_lshl_add_u64 v[10:11], s[4:5], 0, v[0:1]
	ds_read_b32 v0, v7
	ds_read_b32 v12, v7 offset:132
	s_mov_b64 s[4:5], 0x15c0000
	v_lshl_add_u64 v[10:11], v[10:11], 0, s[4:5]
	s_waitcnt lgkmcnt(0)
	v_bfe_u32 v13, v0, 16, 1
	v_add3_u32 v0, v0, v13, s44
	v_bfe_u32 v13, v12, 16, 1
	v_lshrrev_b32_e32 v0, 16, v0
	v_add3_u32 v12, v12, v13, s44
	v_and_or_b32 v16, v12, s49, v0
	ds_read_b32 v0, v7 offset:264
	ds_read_b32 v12, v7 offset:396
	s_waitcnt lgkmcnt(1)
	v_bfe_u32 v13, v0, 16, 1
	v_add3_u32 v0, v0, v13, s44
	s_waitcnt lgkmcnt(0)
	v_bfe_u32 v13, v12, 16, 1
	v_lshrrev_b32_e32 v0, 16, v0
	v_add3_u32 v12, v12, v13, s44
	v_and_or_b32 v17, v12, s49, v0
	ds_read_b32 v0, v7 offset:528
	ds_read_b32 v12, v7 offset:660
	s_waitcnt lgkmcnt(1)
	v_bfe_u32 v13, v0, 16, 1
	v_add3_u32 v0, v0, v13, s44
	s_waitcnt lgkmcnt(0)
	v_bfe_u32 v13, v12, 16, 1
	v_lshrrev_b32_e32 v0, 16, v0
	v_add3_u32 v12, v12, v13, s44
	v_and_or_b32 v18, v12, s49, v0
	ds_read_b32 v0, v7 offset:792
	ds_read_b32 v12, v7 offset:924
	s_waitcnt lgkmcnt(1)
	v_bfe_u32 v13, v0, 16, 1
	v_add3_u32 v0, v0, v13, s44
	s_waitcnt lgkmcnt(0)
	v_bfe_u32 v13, v12, 16, 1
	v_lshrrev_b32_e32 v0, 16, v0
	v_add3_u32 v12, v12, v13, s44
	v_and_or_b32 v19, v12, s49, v0
	v_or_b32_e32 v0, s30, v5
	v_lshlrev_b32_e32 v0, 8, v0
	v_lshl_add_u64 v[12:13], v[10:11], 0, v[0:1]
	flat_store_dwordx4 v[12:13], v[16:19]
	ds_read_b32 v0, v7 offset:32
	ds_read_b32 v12, v7 offset:164
	s_waitcnt lgkmcnt(0)
	v_bfe_u32 v13, v0, 16, 1
	v_add3_u32 v0, v0, v13, s44
	v_bfe_u32 v13, v12, 16, 1
	v_lshrrev_b32_e32 v0, 16, v0
	v_add3_u32 v12, v12, v13, s44
	v_and_or_b32 v16, v12, s49, v0
	ds_read_b32 v0, v7 offset:296
	ds_read_b32 v12, v7 offset:428
	s_waitcnt lgkmcnt(0)
	v_bfe_u32 v13, v0, 16, 1
	v_add3_u32 v0, v0, v13, s44
	v_bfe_u32 v13, v12, 16, 1
	v_lshrrev_b32_e32 v0, 16, v0
	v_add3_u32 v12, v12, v13, s44
	v_and_or_b32 v17, v12, s49, v0
	ds_read_b32 v0, v7 offset:560
	ds_read_b32 v12, v7 offset:692
	s_waitcnt lgkmcnt(0)
	v_bfe_u32 v13, v0, 16, 1
	v_add3_u32 v0, v0, v13, s44
	v_bfe_u32 v13, v12, 16, 1
	v_lshrrev_b32_e32 v0, 16, v0
	v_add3_u32 v12, v12, v13, s44
	v_and_or_b32 v18, v12, s49, v0
	ds_read_b32 v0, v7 offset:824
	ds_read_b32 v12, v7 offset:956
	s_waitcnt lgkmcnt(0)
	v_bfe_u32 v13, v0, 16, 1
	v_add3_u32 v0, v0, v13, s44
	v_bfe_u32 v13, v12, 16, 1
	v_lshrrev_b32_e32 v0, 16, v0
	v_add3_u32 v12, v12, v13, s44
	v_and_or_b32 v19, v12, s49, v0
	v_or_b32_e32 v0, s30, v9
	v_lshlrev_b32_e32 v0, 8, v0
	v_lshl_add_u64 v[12:13], v[10:11], 0, v[0:1]
	flat_store_dwordx4 v[12:13], v[16:19]
	ds_read_b32 v0, v7 offset:64
	ds_read_b32 v12, v7 offset:196
	s_waitcnt lgkmcnt(0)
	v_bfe_u32 v13, v0, 16, 1
	v_add3_u32 v0, v0, v13, s44
	v_bfe_u32 v13, v12, 16, 1
	v_lshrrev_b32_e32 v0, 16, v0
	v_add3_u32 v12, v12, v13, s44
	v_and_or_b32 v16, v12, s49, v0
	ds_read_b32 v0, v7 offset:328
	ds_read_b32 v12, v7 offset:460
	s_waitcnt lgkmcnt(0)
	v_bfe_u32 v13, v0, 16, 1
	v_add3_u32 v0, v0, v13, s44
	v_bfe_u32 v13, v12, 16, 1
	v_lshrrev_b32_e32 v0, 16, v0
	v_add3_u32 v12, v12, v13, s44
	v_and_or_b32 v17, v12, s49, v0
	ds_read_b32 v0, v7 offset:592
	ds_read_b32 v12, v7 offset:724
	s_waitcnt lgkmcnt(0)
	v_bfe_u32 v13, v0, 16, 1
	v_add3_u32 v0, v0, v13, s44
	v_bfe_u32 v13, v12, 16, 1
	v_lshrrev_b32_e32 v0, 16, v0
	v_add3_u32 v12, v12, v13, s44
	v_and_or_b32 v18, v12, s49, v0
	ds_read_b32 v0, v7 offset:856
	ds_read_b32 v12, v7 offset:988
	s_waitcnt lgkmcnt(0)
	v_bfe_u32 v13, v0, 16, 1
	v_add3_u32 v0, v0, v13, s44
	v_bfe_u32 v13, v12, 16, 1
	v_lshrrev_b32_e32 v0, 16, v0
	v_add3_u32 v12, v12, v13, s44
	v_and_or_b32 v19, v12, s49, v0
	v_or_b32_e32 v0, s30, v14
	v_lshlrev_b32_e32 v0, 8, v0
	v_lshl_add_u64 v[12:13], v[10:11], 0, v[0:1]
	flat_store_dwordx4 v[12:13], v[16:19]
	ds_read_b32 v0, v7 offset:96
	ds_read_b32 v12, v7 offset:228
	s_waitcnt lgkmcnt(0)
	v_bfe_u32 v13, v0, 16, 1
	v_add3_u32 v0, v0, v13, s44
	v_bfe_u32 v13, v12, 16, 1
	v_lshrrev_b32_e32 v0, 16, v0
	v_add3_u32 v12, v12, v13, s44
	v_and_or_b32 v16, v12, s49, v0
	ds_read_b32 v0, v7 offset:360
	ds_read_b32 v12, v7 offset:492
	s_waitcnt lgkmcnt(0)
	v_bfe_u32 v13, v0, 16, 1
	v_add3_u32 v0, v0, v13, s44
	v_bfe_u32 v13, v12, 16, 1
	v_lshrrev_b32_e32 v0, 16, v0
	v_add3_u32 v12, v12, v13, s44
	v_and_or_b32 v17, v12, s49, v0
	ds_read_b32 v0, v7 offset:624
	ds_read_b32 v12, v7 offset:756
	s_waitcnt lgkmcnt(0)
	v_bfe_u32 v13, v0, 16, 1
	v_add3_u32 v0, v0, v13, s44
	v_bfe_u32 v13, v12, 16, 1
	v_lshrrev_b32_e32 v0, 16, v0
	v_add3_u32 v12, v12, v13, s44
	v_and_or_b32 v18, v12, s49, v0
	ds_read_b32 v0, v7 offset:888
	ds_read_b32 v12, v7 offset:1020
	s_waitcnt lgkmcnt(0)
	v_bfe_u32 v13, v0, 16, 1
	v_add3_u32 v0, v0, v13, s44
	v_bfe_u32 v13, v12, 16, 1
	v_lshrrev_b32_e32 v0, 16, v0
	v_add3_u32 v12, v12, v13, s44
	v_and_or_b32 v19, v12, s49, v0
	v_or_b32_e32 v0, s30, v15
	v_lshlrev_b32_e32 v0, 8, v0
	v_lshl_add_u64 v[10:11], v[10:11], 0, v[0:1]
	flat_store_dwordx4 v[10:11], v[16:19]
	s_waitcnt lgkmcnt(0)

; __device__ __forceinline__ void transpose_item(const float* W, int K, int N, bf16_t* WT, int k0, int n0, int drow0, LAS float* scr, int lane) {
;     ...
;     for (int i = 0; i < 32; ++i) { const int kk = 2 * i + (lane >> 5); scr[kk * 33 + (lane & 31)] = W[(size_t)(k0 + kk) * N + n0 + (lane & 31)]; }
;     asm volatile("s_waitcnt lgkmcnt(0)" ::: "memory");
.LBB0_459:
	s_lshl_b32 s24, s15, 1
	s_lshl_b32 s23, s14, 1
	v_or_b32_e32 v18, s24, v2
	v_or_b32_e32 v0, s23, v3
	v_add_u32_e32 v12, s4, v18
	v_add_u32_e32 v16, s5, v0
	v_mad_u64_u32 v[12:13], s[26:27], v12, s47, v[10:11]
	v_mad_u64_u32 v[16:17], s[26:27], v16, s47, v[10:11]
	global_load_dword v22, v[12:13], off
	global_load_dword v23, v[16:17], off
	v_mad_u64_u32 v[52:53], s[26:27], v18, s50, v[6:7]
	v_mad_u64_u32 v[54:55], s[26:27], v0, s50, v[6:7]
	s_add_i32 s26, s24, 4
	s_add_i32 s25, s23, 4
	v_or_b32_e32 v18, s26, v2
	v_or_b32_e32 v0, s25, v3
	s_add_i32 s25, s23, 8
	s_add_i32 s15, s15, 16
	s_add_i32 s14, s14, 16
	s_add_i32 s22, s22, -16
	v_add_u32_e32 v12, s4, v18
	v_add_u32_e32 v16, s5, v0
	v_mad_u64_u32 v[12:13], s[26:27], v12, s47, v[10:11]
	v_mad_u64_u32 v[16:17], s[26:27], v16, s47, v[10:11]
	global_load_dword v24, v[12:13], off
	global_load_dword v25, v[16:17], off
	v_mad_u64_u32 v[56:57], s[26:27], v18, s50, v[6:7]
	v_mad_u64_u32 v[58:59], s[26:27], v0, s50, v[6:7]
	s_add_i32 s26, s24, 8
	s_nop 0
	v_or_b32_e32 v18, s26, v2
	v_or_b32_e32 v0, s25, v3
	s_add_i32 s25, s23, 12
	v_add_u32_e32 v12, s4, v18
	v_add_u32_e32 v16, s5, v0
	v_mad_u64_u32 v[12:13], s[26:27], v12, s47, v[10:11]
	v_mad_u64_u32 v[16:17], s[26:27], v16, s47, v[10:11]
	global_load_dword v26, v[12:13], off
	global_load_dword v27, v[16:17], off
	v_mad_u64_u32 v[60:61], s[26:27], v18, s50, v[6:7]
	v_mad_u64_u32 v[62:63], s[26:27], v0, s50, v[6:7]
	s_add_i32 s26, s24, 12
	s_nop 0
	v_or_b32_e32 v18, s26, v2
	v_or_b32_e32 v0, s25, v3
	s_add_i32 s25, s23, 16
	v_add_u32_e32 v12, s4, v18
	v_add_u32_e32 v16, s5, v0
	v_mad_u64_u32 v[12:13], s[26:27], v12, s47, v[10:11]
	v_mad_u64_u32 v[16:17], s[26:27], v16, s47, v[10:11]
	global_load_dword v28, v[12:13], off
	global_load_dword v29, v[16:17], off
	v_mad_u64_u32 v[64:65], s[26:27], v18, s50, v[6:7]
	v_mad_u64_u32 v[66:67], s[26:27], v0, s50, v[6:7]
	s_add_i32 s26, s24, 16
	s_nop 0
	v_or_b32_e32 v18, s26, v2
	v_or_b32_e32 v0, s25, v3
	s_add_i32 s25, s23, 20
	v_add_u32_e32 v12, s4, v18
	v_add_u32_e32 v16, s5, v0
	v_mad_u64_u32 v[12:13], s[26:27], v12, s47, v[10:11]
	v_mad_u64_u32 v[16:17], s[26:27], v16, s47, v[10:11]
	global_load_dword v30, v[12:13], off
	global_load_dword v31, v[16:17], off
	v_mad_u64_u32 v[68:69], s[26:27], v18, s50, v[6:7]
	v_mad_u64_u32 v[70:71], s[26:27], v0, s50, v[6:7]
	s_add_i32 s26, s24, 20
	s_nop 0
	v_or_b32_e32 v18, s26, v2
	v_or_b32_e32 v0, s25, v3
	s_add_i32 s25, s23, 24
	s_add_i32 s23, s23, 28
	v_add_u32_e32 v12, s4, v18
	v_add_u32_e32 v16, s5, v0
	v_mad_u64_u32 v[12:13], s[26:27], v12, s47, v[10:11]
	v_mad_u64_u32 v[16:17], s[26:27], v16, s47, v[10:11]
	global_load_dword v32, v[12:13], off
	global_load_dword v33, v[16:17], off
	v_mad_u64_u32 v[72:73], s[26:27], v18, s50, v[6:7]
	v_mad_u64_u32 v[74:75], s[26:27], v0, s50, v[6:7]
	s_add_i32 s26, s24, 24
	s_nop 0
	v_or_b32_e32 v18, s26, v2
	v_or_b32_e32 v0, s25, v3
	s_add_i32 s24, s24, 28
	s_cmp_lg_u32 s22, 0
	v_add_u32_e32 v12, s4, v18
	v_add_u32_e32 v16, s5, v0
	v_mad_u64_u32 v[12:13], s[26:27], v12, s47, v[10:11]
	v_mad_u64_u32 v[16:17], s[26:27], v16, s47, v[10:11]
	global_load_dword v34, v[12:13], off
	global_load_dword v35, v[16:17], off
	v_mad_u64_u32 v[76:77], s[26:27], v18, s50, v[6:7]
	v_or_b32_e32 v18, s24, v2
	v_mad_u64_u32 v[78:79], s[26:27], v0, s50, v[6:7]
	v_or_b32_e32 v0, s23, v3
	v_add_u32_e32 v12, s4, v18
	v_add_u32_e32 v16, s5, v0
	v_mad_u64_u32 v[12:13], s[24:25], v12, s47, v[10:11]
	v_mad_u64_u32 v[16:17], s[24:25], v16, s47, v[10:11]
	global_load_dword v36, v[12:13], off
	global_load_dword v37, v[16:17], off
	v_mad_u64_u32 v[80:81], s[24:25], v18, s50, v[6:7]
	v_mad_u64_u32 v[82:83], s[24:25], v0, s50, v[6:7]
	s_waitcnt vmcnt(15)
	ds_write_b32 v52, v22
	s_waitcnt vmcnt(14)
	ds_write_b32 v54, v23
	s_waitcnt vmcnt(13)
	ds_write_b32 v56, v24
	s_waitcnt vmcnt(12)
	ds_write_b32 v58, v25
	s_waitcnt vmcnt(11)
	ds_write_b32 v60, v26
	s_waitcnt vmcnt(10)
	ds_write_b32 v62, v27
	s_waitcnt vmcnt(9)
	ds_write_b32 v64, v28
	s_waitcnt vmcnt(8)
	ds_write_b32 v66, v29
	s_waitcnt vmcnt(7)
	ds_write_b32 v68, v30
	s_waitcnt vmcnt(6)
	ds_write_b32 v70, v31
	s_waitcnt vmcnt(5)
	ds_write_b32 v72, v32
	s_waitcnt vmcnt(4)
	ds_write_b32 v74, v33
	s_waitcnt vmcnt(3)
	ds_write_b32 v76, v34
	s_waitcnt vmcnt(2)
	ds_write_b32 v78, v35
	s_waitcnt vmcnt(1)
	ds_write_b32 v80, v36
	s_waitcnt vmcnt(0)
	ds_write_b32 v82, v37
	s_cbranch_scc1 .LBB0_459
; #define LAS __attribute__((address_space(3)))
; __device__ __forceinline__ unsigned pk2(float lo, float hi) { return f2bf(lo) | (f2bf(hi) << 16); }
; __device__ __forceinline__ void transpose_item(const float* W, int K, int N, bf16_t* WT, int k0, int n0, int drow0, LAS float* scr, int lane) {
;     ...
;     const int c = lane & 7;
; #pragma unroll
;     for (int j = 0; j < 4; ++j) { const int n = (lane >> 3) + 8 * j; const LAS float* s = scr + (8 * c) * 33 + n;
;         u32x4 o; o.x = pk2(s[0 * 33], s[1 * 33]); o.y = pk2(s[2 * 33], s[3 * 33]); o.z = pk2(s[4 * 33], s[5 * 33]); o.w = pk2(s[6 * 33], s[7 * 33]);
;         *(u32x4*)(WT + (size_t)(drow0 + n) * K + k0 + 8 * c) = o; }
;     asm volatile("s_waitcnt lgkmcnt(0)" ::: "memory");
	s_lshl_b32 s4, s4, 1
	s_add_u32 s4, s7, s4
	s_waitcnt lgkmcnt(0)
	s_addc_u32 s5, s8, 0
	v_lshlrev_b32_e32 v0, 1, v8
	v_lshl_add_u64 v[10:11], s[4:5], 0, v[0:1]
	ds_read_b32 v0, v7
	ds_read_b32 v12, v7 offset:132
	s_mov_b64 s[4:5], 0x1580000
	v_lshl_add_u64 v[10:11], v[10:11], 0, s[4:5]
	s_waitcnt lgkmcnt(0)
	v_bfe_u32 v13, v0, 16, 1
	v_add3_u32 v0, v0, v13, s44
	v_bfe_u32 v13, v12, 16, 1
	v_lshrrev_b32_e32 v0, 16, v0
	v_add3_u32 v12, v12, v13, s44
	v_and_or_b32 v16, v12, s49, v0
	ds_read_b32 v0, v7 offset:264
	ds_read_b32 v12, v7 offset:396
	s_waitcnt lgkmcnt(1)
	v_bfe_u32 v13, v0, 16, 1
	v_add3_u32 v0, v0, v13, s44
	s_waitcnt lgkmcnt(0)
	v_bfe_u32 v13, v12, 16, 1
	v_lshrrev_b32_e32 v0, 16, v0
	v_add3_u32 v12, v12, v13, s44
	v_and_or_b32 v17, v12, s49, v0
	ds_read_b32 v0, v7 offset:528
	ds_read_b32 v12, v7 offset:660
	s_waitcnt lgkmcnt(1)
	v_bfe_u32 v13, v0, 16, 1
	v_add3_u32 v0, v0, v13, s44
	s_waitcnt lgkmcnt(0)
	v_bfe_u32 v13, v12, 16, 1
	v_lshrrev_b32_e32 v0, 16, v0
	v_add3_u32 v12, v12, v13, s44
	v_and_or_b32 v18, v12, s49, v0
	ds_read_b32 v0, v7 offset:792
	ds_read_b32 v12, v7 offset:924
	s_waitcnt lgkmcnt(1)
	v_bfe_u32 v13, v0, 16, 1
	v_add3_u32 v0, v0, v13, s44
	s_waitcnt lgkmcnt(0)
	v_bfe_u32 v13, v12, 16, 1
	v_lshrrev_b32_e32 v0, 16, v0
	v_add3_u32 v12, v12, v13, s44
	v_and_or_b32 v19, v12, s49, v0
	v_or_b32_e32 v0, s1, v5
	v_lshlrev_b32_e32 v0, 9, v0
	v_lshl_add_u64 v[12:13], v[10:11], 0, v[0:1]
	flat_store_dwordx4 v[12:13], v[16:19]
	ds_read_b32 v0, v7 offset:32
	ds_read_b32 v12, v7 offset:164
	s_waitcnt lgkmcnt(0)
	v_bfe_u32 v13, v0, 16, 1
	v_add3_u32 v0, v0, v13, s44
	v_bfe_u32 v13, v12, 16, 1
	v_lshrrev_b32_e32 v0, 16, v0
	v_add3_u32 v12, v12, v13, s44
	v_and_or_b32 v16, v12, s49, v0
	ds_read_b32 v0, v7 offset:296
	ds_read_b32 v12, v7 offset:428
	s_waitcnt lgkmcnt(0)
	v_bfe_u32 v13, v0, 16, 1
	v_add3_u32 v0, v0, v13, s44
	v_bfe_u32 v13, v12, 16, 1
	v_lshrrev_b32_e32 v0, 16, v0
	v_add3_u32 v12, v12, v13, s44
	v_and_or_b32 v17, v12, s49, v0
	ds_read_b32 v0, v7 offset:560
	ds_read_b32 v12, v7 offset:692
	s_waitcnt lgkmcnt(0)
	v_bfe_u32 v13, v0, 16, 1
	v_add3_u32 v0, v0, v13, s44
	v_bfe_u32 v13, v12, 16, 1
	v_lshrrev_b32_e32 v0, 16, v0
	v_add3_u32 v12, v12, v13, s44
	v_and_or_b32 v18, v12, s49, v0
	ds_read_b32 v0, v7 offset:824
	ds_read_b32 v12, v7 offset:956
	s_waitcnt lgkmcnt(0)
	v_bfe_u32 v13, v0, 16, 1
	v_add3_u32 v0, v0, v13, s44
	v_bfe_u32 v13, v12, 16, 1
	v_lshrrev_b32_e32 v0, 16, v0
	v_add3_u32 v12, v12, v13, s44
	v_and_or_b32 v19, v12, s49, v0
	v_or_b32_e32 v0, s1, v9
	v_lshlrev_b32_e32 v0, 9, v0
	v_lshl_add_u64 v[12:13], v[10:11], 0, v[0:1]
	flat_store_dwordx4 v[12:13], v[16:19]
	ds_read_b32 v0, v7 offset:64
	ds_read_b32 v12, v7 offset:196
	s_waitcnt lgkmcnt(0)
	v_bfe_u32 v13, v0, 16, 1
	v_add3_u32 v0, v0, v13, s44
	v_bfe_u32 v13, v12, 16, 1
	v_lshrrev_b32_e32 v0, 16, v0
	v_add3_u32 v12, v12, v13, s44
	v_and_or_b32 v16, v12, s49, v0
	ds_read_b32 v0, v7 offset:328
	ds_read_b32 v12, v7 offset:460
	s_waitcnt lgkmcnt(0)
	v_bfe_u32 v13, v0, 16, 1
	v_add3_u32 v0, v0, v13, s44
	v_bfe_u32 v13, v12, 16, 1
	v_lshrrev_b32_e32 v0, 16, v0
	v_add3_u32 v12, v12, v13, s44
	v_and_or_b32 v17, v12, s49, v0
	ds_read_b32 v0, v7 offset:592
	ds_read_b32 v12, v7 offset:724
	s_waitcnt lgkmcnt(0)
	v_bfe_u32 v13, v0, 16, 1
	v_add3_u32 v0, v0, v13, s44
	v_bfe_u32 v13, v12, 16, 1
	v_lshrrev_b32_e32 v0, 16, v0
	v_add3_u32 v12, v12, v13, s44
	v_and_or_b32 v18, v12, s49, v0
	ds_read_b32 v0, v7 offset:856
	ds_read_b32 v12, v7 offset:988
	s_waitcnt lgkmcnt(0)
	v_bfe_u32 v13, v0, 16, 1
	v_add3_u32 v0, v0, v13, s44
	v_bfe_u32 v13, v12, 16, 1
	v_lshrrev_b32_e32 v0, 16, v0
	v_add3_u32 v12, v12, v13, s44
	v_and_or_b32 v19, v12, s49, v0
	v_or_b32_e32 v0, s1, v14
	v_lshlrev_b32_e32 v0, 9, v0
	v_lshl_add_u64 v[12:13], v[10:11], 0, v[0:1]
	flat_store_dwordx4 v[12:13], v[16:19]
	ds_read_b32 v0, v7 offset:96
	ds_read_b32 v12, v7 offset:228
	s_waitcnt lgkmcnt(0)
	v_bfe_u32 v13, v0, 16, 1
	v_add3_u32 v0, v0, v13, s44
	v_bfe_u32 v13, v12, 16, 1
	v_lshrrev_b32_e32 v0, 16, v0
	v_add3_u32 v12, v12, v13, s44
	v_and_or_b32 v16, v12, s49, v0
	ds_read_b32 v0, v7 offset:360
	ds_read_b32 v12, v7 offset:492
	s_waitcnt lgkmcnt(0)
	v_bfe_u32 v13, v0, 16, 1
	v_add3_u32 v0, v0, v13, s44
	v_bfe_u32 v13, v12, 16, 1
	v_lshrrev_b32_e32 v0, 16, v0
	v_add3_u32 v12, v12, v13, s44
	v_and_or_b32 v17, v12, s49, v0
	ds_read_b32 v0, v7 offset:624
	ds_read_b32 v12, v7 offset:756
	s_waitcnt lgkmcnt(0)
	v_bfe_u32 v13, v0, 16, 1
	v_add3_u32 v0, v0, v13, s44
	v_bfe_u32 v13, v12, 16, 1
	v_lshrrev_b32_e32 v0, 16, v0
	v_add3_u32 v12, v12, v13, s44
	v_and_or_b32 v18, v12, s49, v0
	ds_read_b32 v0, v7 offset:888
	ds_read_b32 v12, v7 offset:1020
	s_waitcnt lgkmcnt(0)
	v_bfe_u32 v13, v0, 16, 1
	v_add3_u32 v0, v0, v13, s44
	v_bfe_u32 v13, v12, 16, 1
	v_lshrrev_b32_e32 v0, 16, v0
	v_add3_u32 v12, v12, v13, s44
	v_and_or_b32 v19, v12, s49, v0
	v_or_b32_e32 v0, s1, v15
	v_lshlrev_b32_e32 v0, 9, v0
	v_lshl_add_u64 v[10:11], v[10:11], 0, v[0:1]
	flat_store_dwordx4 v[10:11], v[16:19]
	s_waitcnt lgkmcnt(0)

; __device__ __forceinline__ void transpose_item(const float* W, int K, int N, bf16_t* WT, int k0, int n0, int drow0, LAS float* scr, int lane) {
;     ...
;     for (int i = 0; i < 32; ++i) { const int kk = 2 * i + (lane >> 5); scr[kk * 33 + (lane & 31)] = W[(size_t)(k0 + kk) * N + n0 + (lane & 31)]; }
;     asm volatile("s_waitcnt lgkmcnt(0)" ::: "memory");
.LBB0_464:
	s_lshl_b32 s24, s15, 1
	s_lshl_b32 s23, s14, 1
	v_or_b32_e32 v18, s24, v2
	v_or_b32_e32 v0, s23, v3
	v_add_u32_e32 v12, s1, v18
	v_add_u32_e32 v16, s5, v0
	v_mad_u64_u32 v[12:13], s[26:27], v12, s48, v[10:11]
	v_mad_u64_u32 v[16:17], s[26:27], v16, s48, v[10:11]
	global_load_dword v22, v[12:13], off
	global_load_dword v23, v[16:17], off
	v_mad_u64_u32 v[52:53], s[26:27], v18, s50, v[6:7]
	v_mad_u64_u32 v[54:55], s[26:27], v0, s50, v[6:7]
	s_add_i32 s26, s24, 4
	s_add_i32 s25, s23, 4
	v_or_b32_e32 v18, s26, v2
	v_or_b32_e32 v0, s25, v3
	s_add_i32 s25, s23, 8
	s_add_i32 s15, s15, 16
	s_add_i32 s14, s14, 16
	s_add_i32 s22, s22, -16
	v_add_u32_e32 v12, s1, v18
	v_add_u32_e32 v16, s5, v0
	v_mad_u64_u32 v[12:13], s[26:27], v12, s48, v[10:11]
	v_mad_u64_u32 v[16:17], s[26:27], v16, s48, v[10:11]
	global_load_dword v24, v[12:13], off
	global_load_dword v25, v[16:17], off
	v_mad_u64_u32 v[56:57], s[26:27], v18, s50, v[6:7]
	v_mad_u64_u32 v[58:59], s[26:27], v0, s50, v[6:7]
	s_add_i32 s26, s24, 8
	s_nop 0
	v_or_b32_e32 v18, s26, v2
	v_or_b32_e32 v0, s25, v3
	s_add_i32 s25, s23, 12
	v_add_u32_e32 v12, s1, v18
	v_add_u32_e32 v16, s5, v0
	v_mad_u64_u32 v[12:13], s[26:27], v12, s48, v[10:11]
	v_mad_u64_u32 v[16:17], s[26:27], v16, s48, v[10:11]
	global_load_dword v26, v[12:13], off
	global_load_dword v27, v[16:17], off
	v_mad_u64_u32 v[60:61], s[26:27], v18, s50, v[6:7]
	v_mad_u64_u32 v[62:63], s[26:27], v0, s50, v[6:7]
	s_add_i32 s26, s24, 12
	s_nop 0
	v_or_b32_e32 v18, s26, v2
	v_or_b32_e32 v0, s25, v3
	s_add_i32 s25, s23, 16
	v_add_u32_e32 v12, s1, v18
	v_add_u32_e32 v16, s5, v0
	v_mad_u64_u32 v[12:13], s[26:27], v12, s48, v[10:11]
	v_mad_u64_u32 v[16:17], s[26:27], v16, s48, v[10:11]
	global_load_dword v28, v[12:13], off
	global_load_dword v29, v[16:17], off
	v_mad_u64_u32 v[64:65], s[26:27], v18, s50, v[6:7]
	v_mad_u64_u32 v[66:67], s[26:27], v0, s50, v[6:7]
	s_add_i32 s26, s24, 16
	s_nop 0
	v_or_b32_e32 v18, s26, v2
	v_or_b32_e32 v0, s25, v3
	s_add_i32 s25, s23, 20
	v_add_u32_e32 v12, s1, v18
	v_add_u32_e32 v16, s5, v0
	v_mad_u64_u32 v[12:13], s[26:27], v12, s48, v[10:11]
	v_mad_u64_u32 v[16:17], s[26:27], v16, s48, v[10:11]
	global_load_dword v30, v[12:13], off
	global_load_dword v31, v[16:17], off
	v_mad_u64_u32 v[68:69], s[26:27], v18, s50, v[6:7]
	v_mad_u64_u32 v[70:71], s[26:27], v0, s50, v[6:7]
	s_add_i32 s26, s24, 20
	s_nop 0
	v_or_b32_e32 v18, s26, v2
	v_or_b32_e32 v0, s25, v3
	s_add_i32 s25, s23, 24
	s_add_i32 s23, s23, 28
	v_add_u32_e32 v12, s1, v18
	v_add_u32_e32 v16, s5, v0
	v_mad_u64_u32 v[12:13], s[26:27], v12, s48, v[10:11]
	v_mad_u64_u32 v[16:17], s[26:27], v16, s48, v[10:11]
	global_load_dword v32, v[12:13], off
	global_load_dword v33, v[16:17], off
	v_mad_u64_u32 v[72:73], s[26:27], v18, s50, v[6:7]
	v_mad_u64_u32 v[74:75], s[26:27], v0, s50, v[6:7]
	s_add_i32 s26, s24, 24
	s_nop 0
	v_or_b32_e32 v18, s26, v2
	v_or_b32_e32 v0, s25, v3
	s_add_i32 s24, s24, 28
	s_cmp_lg_u32 s22, 0
	v_add_u32_e32 v12, s1, v18
	v_add_u32_e32 v16, s5, v0
	v_mad_u64_u32 v[12:13], s[26:27], v12, s48, v[10:11]
	v_mad_u64_u32 v[16:17], s[26:27], v16, s48, v[10:11]
	global_load_dword v34, v[12:13], off
	global_load_dword v35, v[16:17], off
	v_mad_u64_u32 v[76:77], s[26:27], v18, s50, v[6:7]
	v_or_b32_e32 v18, s24, v2
	v_mad_u64_u32 v[78:79], s[26:27], v0, s50, v[6:7]
	v_or_b32_e32 v0, s23, v3
	v_add_u32_e32 v12, s1, v18
	v_add_u32_e32 v16, s5, v0
	v_mad_u64_u32 v[12:13], s[24:25], v12, s48, v[10:11]
	v_mad_u64_u32 v[16:17], s[24:25], v16, s48, v[10:11]
	global_load_dword v36, v[12:13], off
	global_load_dword v37, v[16:17], off
	v_mad_u64_u32 v[80:81], s[24:25], v18, s50, v[6:7]
	v_mad_u64_u32 v[82:83], s[24:25], v0, s50, v[6:7]
	s_waitcnt vmcnt(15)
	ds_write_b32 v52, v22
	s_waitcnt vmcnt(14)
	ds_write_b32 v54, v23
	s_waitcnt vmcnt(13)
	ds_write_b32 v56, v24
	s_waitcnt vmcnt(12)
	ds_write_b32 v58, v25
	s_waitcnt vmcnt(11)
	ds_write_b32 v60, v26
	s_waitcnt vmcnt(10)
	ds_write_b32 v62, v27
	s_waitcnt vmcnt(9)
	ds_write_b32 v64, v28
	s_waitcnt vmcnt(8)
	ds_write_b32 v66, v29
	s_waitcnt vmcnt(7)
	ds_write_b32 v68, v30
	s_waitcnt vmcnt(6)
	ds_write_b32 v70, v31
	s_waitcnt vmcnt(5)
	ds_write_b32 v72, v32
	s_waitcnt vmcnt(4)
	ds_write_b32 v74, v33
	s_waitcnt vmcnt(3)
	ds_write_b32 v76, v34
	s_waitcnt vmcnt(2)
	ds_write_b32 v78, v35
	s_waitcnt vmcnt(1)
	ds_write_b32 v80, v36
	s_waitcnt vmcnt(0)
	ds_write_b32 v82, v37
	s_cbranch_scc1 .LBB0_464
; #define LAS __attribute__((address_space(3)))
; __device__ __forceinline__ unsigned pk2(float lo, float hi) { return f2bf(lo) | (f2bf(hi) << 16); }
; __device__ __forceinline__ void transpose_item(const float* W, int K, int N, bf16_t* WT, int k0, int n0, int drow0, LAS float* scr, int lane) {
;     ...
;     const int c = lane & 7;
; #pragma unroll
;     for (int j = 0; j < 4; ++j) { const int n = (lane >> 3) + 8 * j; const LAS float* s = scr + (8 * c) * 33 + n;
;         u32x4 o; o.x = pk2(s[0 * 33], s[1 * 33]); o.y = pk2(s[2 * 33], s[3 * 33]); o.z = pk2(s[4 * 33], s[5 * 33]); o.w = pk2(s[6 * 33], s[7 * 33]);
;         *(u32x4*)(WT + (size_t)(drow0 + n) * K + k0 + 8 * c) = o; }
;     asm volatile("s_waitcnt lgkmcnt(0)" ::: "memory");
	s_and_b32 s1, 0xffff, s1
	s_and_b32 s4, 0xffff, s4
	s_lshl_b32 s1, s1, 1
	s_add_u32 s14, s7, s1
	s_waitcnt lgkmcnt(0)
	s_addc_u32 s15, s8, 0
	v_lshlrev_b32_e32 v0, 1, v8
	v_lshl_add_u64 v[10:11], s[14:15], 0, v[0:1]
	ds_read_b32 v0, v7
	ds_read_b32 v12, v7 offset:132
	s_mov_b64 s[14:15], 0x1080000
	v_lshl_add_u64 v[10:11], v[10:11], 0, s[14:15]
	s_waitcnt lgkmcnt(0)
	v_bfe_u32 v13, v0, 16, 1
	v_add3_u32 v0, v0, v13, s44
	v_bfe_u32 v13, v12, 16, 1
	v_lshrrev_b32_e32 v0, 16, v0
	v_add3_u32 v12, v12, v13, s44
	v_and_or_b32 v16, v12, s49, v0
	ds_read_b32 v0, v7 offset:264
	ds_read_b32 v12, v7 offset:396
	s_waitcnt lgkmcnt(1)
	v_bfe_u32 v13, v0, 16, 1
	v_add3_u32 v0, v0, v13, s44
	s_waitcnt lgkmcnt(0)
	v_bfe_u32 v13, v12, 16, 1
	v_lshrrev_b32_e32 v0, 16, v0
	v_add3_u32 v12, v12, v13, s44
	v_and_or_b32 v17, v12, s49, v0
	ds_read_b32 v0, v7 offset:528
	ds_read_b32 v12, v7 offset:660
	s_waitcnt lgkmcnt(1)
	v_bfe_u32 v13, v0, 16, 1
	v_add3_u32 v0, v0, v13, s44
	s_waitcnt lgkmcnt(0)
	v_bfe_u32 v13, v12, 16, 1
	v_lshrrev_b32_e32 v0, 16, v0
	v_add3_u32 v12, v12, v13, s44
	v_and_or_b32 v18, v12, s49, v0
	ds_read_b32 v0, v7 offset:792
	ds_read_b32 v12, v7 offset:924
	s_waitcnt lgkmcnt(1)
	v_bfe_u32 v13, v0, 16, 1
	v_add3_u32 v0, v0, v13, s44
	s_waitcnt lgkmcnt(0)
	v_bfe_u32 v13, v12, 16, 1
	v_lshrrev_b32_e32 v0, 16, v0
	v_add3_u32 v12, v12, v13, s44
	v_and_or_b32 v19, v12, s49, v0
	v_or_b32_e32 v0, s4, v5
	v_lshlrev_b32_e32 v0, 11, v0
	v_lshl_add_u64 v[12:13], v[10:11], 0, v[0:1]
	flat_store_dwordx4 v[12:13], v[16:19]
	ds_read_b32 v0, v7 offset:32
	ds_read_b32 v12, v7 offset:164
	s_waitcnt lgkmcnt(0)
	v_bfe_u32 v13, v0, 16, 1
	v_add3_u32 v0, v0, v13, s44
	v_bfe_u32 v13, v12, 16, 1
	v_lshrrev_b32_e32 v0, 16, v0
	v_add3_u32 v12, v12, v13, s44
	v_and_or_b32 v16, v12, s49, v0
	ds_read_b32 v0, v7 offset:296
	ds_read_b32 v12, v7 offset:428
	s_waitcnt lgkmcnt(0)
	v_bfe_u32 v13, v0, 16, 1
	v_add3_u32 v0, v0, v13, s44
	v_bfe_u32 v13, v12, 16, 1
	v_lshrrev_b32_e32 v0, 16, v0
	v_add3_u32 v12, v12, v13, s44
	v_and_or_b32 v17, v12, s49, v0
	ds_read_b32 v0, v7 offset:560
	ds_read_b32 v12, v7 offset:692
	s_waitcnt lgkmcnt(0)
	v_bfe_u32 v13, v0, 16, 1
	v_add3_u32 v0, v0, v13, s44
	v_bfe_u32 v13, v12, 16, 1
	v_lshrrev_b32_e32 v0, 16, v0
	v_add3_u32 v12, v12, v13, s44
	v_and_or_b32 v18, v12, s49, v0
	ds_read_b32 v0, v7 offset:824
	ds_read_b32 v12, v7 offset:956
	s_waitcnt lgkmcnt(0)
	v_bfe_u32 v13, v0, 16, 1
	v_add3_u32 v0, v0, v13, s44
	v_bfe_u32 v13, v12, 16, 1
	v_lshrrev_b32_e32 v0, 16, v0
	v_add3_u32 v12, v12, v13, s44
	v_and_or_b32 v19, v12, s49, v0
	v_or_b32_e32 v0, s4, v9
	v_lshlrev_b32_e32 v0, 11, v0
	v_lshl_add_u64 v[12:13], v[10:11], 0, v[0:1]
	flat_store_dwordx4 v[12:13], v[16:19]
	ds_read_b32 v0, v7 offset:64
	ds_read_b32 v12, v7 offset:196
	s_waitcnt lgkmcnt(0)
	v_bfe_u32 v13, v0, 16, 1
	v_add3_u32 v0, v0, v13, s44
	v_bfe_u32 v13, v12, 16, 1
	v_lshrrev_b32_e32 v0, 16, v0
	v_add3_u32 v12, v12, v13, s44
	v_and_or_b32 v16, v12, s49, v0
	ds_read_b32 v0, v7 offset:328
	ds_read_b32 v12, v7 offset:460
	s_waitcnt lgkmcnt(0)
	v_bfe_u32 v13, v0, 16, 1
	v_add3_u32 v0, v0, v13, s44
	v_bfe_u32 v13, v12, 16, 1
	v_lshrrev_b32_e32 v0, 16, v0
	v_add3_u32 v12, v12, v13, s44
	v_and_or_b32 v17, v12, s49, v0
	ds_read_b32 v0, v7 offset:592
	ds_read_b32 v12, v7 offset:724
	s_waitcnt lgkmcnt(0)
	v_bfe_u32 v13, v0, 16, 1
	v_add3_u32 v0, v0, v13, s44
	v_bfe_u32 v13, v12, 16, 1
	v_lshrrev_b32_e32 v0, 16, v0
	v_add3_u32 v12, v12, v13, s44
	v_and_or_b32 v18, v12, s49, v0
	ds_read_b32 v0, v7 offset:856
	ds_read_b32 v12, v7 offset:988
	s_waitcnt lgkmcnt(0)
	v_bfe_u32 v13, v0, 16, 1
	v_add3_u32 v0, v0, v13, s44
	v_bfe_u32 v13, v12, 16, 1
	v_lshrrev_b32_e32 v0, 16, v0
	v_add3_u32 v12, v12, v13, s44
	v_and_or_b32 v19, v12, s49, v0
	v_or_b32_e32 v0, s4, v14
	v_lshlrev_b32_e32 v0, 11, v0
	v_lshl_add_u64 v[12:13], v[10:11], 0, v[0:1]
	flat_store_dwordx4 v[12:13], v[16:19]
	ds_read_b32 v0, v7 offset:96
	ds_read_b32 v12, v7 offset:228
	s_waitcnt lgkmcnt(0)
	v_bfe_u32 v13, v0, 16, 1
	v_add3_u32 v0, v0, v13, s44
	v_bfe_u32 v13, v12, 16, 1
	v_lshrrev_b32_e32 v0, 16, v0
	v_add3_u32 v12, v12, v13, s44
	v_and_or_b32 v16, v12, s49, v0
	ds_read_b32 v0, v7 offset:360
	ds_read_b32 v12, v7 offset:492
	s_waitcnt lgkmcnt(0)
	v_bfe_u32 v13, v0, 16, 1
	v_add3_u32 v0, v0, v13, s44
	v_bfe_u32 v13, v12, 16, 1
	v_lshrrev_b32_e32 v0, 16, v0
	v_add3_u32 v12, v12, v13, s44
	v_and_or_b32 v17, v12, s49, v0
	ds_read_b32 v0, v7 offset:624
	ds_read_b32 v12, v7 offset:756
	s_waitcnt lgkmcnt(0)
	v_bfe_u32 v13, v0, 16, 1
	v_add3_u32 v0, v0, v13, s44
	v_bfe_u32 v13, v12, 16, 1
	v_lshrrev_b32_e32 v0, 16, v0
	v_add3_u32 v12, v12, v13, s44
	v_and_or_b32 v18, v12, s49, v0
	ds_read_b32 v0, v7 offset:888
	ds_read_b32 v12, v7 offset:1020
	s_waitcnt lgkmcnt(0)
	v_bfe_u32 v13, v0, 16, 1
	v_add3_u32 v0, v0, v13, s44
	v_bfe_u32 v13, v12, 16, 1
	v_lshrrev_b32_e32 v0, 16, v0
	v_add3_u32 v12, v12, v13, s44
	v_and_or_b32 v19, v12, s49, v0
	v_or_b32_e32 v0, s4, v15
	v_lshlrev_b32_e32 v0, 11, v0
	v_lshl_add_u64 v[10:11], v[10:11], 0, v[0:1]
	flat_store_dwordx4 v[10:11], v[16:19]
	s_waitcnt lgkmcnt(0)

; __device__ __forceinline__ void transpose_item(const float* W, int K, int N, bf16_t* WT, int k0, int n0, int drow0, LAS float* scr, int lane) {
;     ...
;     for (int i = 0; i < 32; ++i) { const int kk = 2 * i + (lane >> 5); scr[kk * 33 + (lane & 31)] = W[(size_t)(k0 + kk) * N + n0 + (lane & 31)]; }
;     asm volatile("s_waitcnt lgkmcnt(0)" ::: "memory");
.LBB0_469:
	s_lshl_b32 s24, s15, 1
	s_lshl_b32 s23, s4, 1
	v_or_b32_e32 v19, s24, v2
	v_or_b32_e32 v18, s23, v3
	v_add_u32_e32 v0, s5, v19
	v_add_u32_e32 v12, s14, v18
	v_mov_b32_e32 v13, v1
	v_lshlrev_b64 v[16:17], 12, v[0:1]
	v_lshlrev_b64 v[12:13], 12, v[12:13]
	v_lshl_add_u64 v[16:17], v[10:11], 0, v[16:17]
	v_lshl_add_u64 v[12:13], v[10:11], 0, v[12:13]
	global_load_dword v22, v[16:17], off
	global_load_dword v23, v[12:13], off
	v_mad_u64_u32 v[52:53], s[26:27], v19, s50, v[6:7]
	v_mad_u64_u32 v[54:55], s[26:27], v18, s50, v[6:7]
	s_add_i32 s26, s24, 4
	s_add_i32 s25, s23, 4
	v_or_b32_e32 v19, s26, v2
	v_or_b32_e32 v18, s25, v3
	v_mov_b32_e32 v13, v1
	s_add_i32 s25, s23, 8
	s_add_i32 s15, s15, 16
	s_add_i32 s4, s4, 16
	s_add_i32 s22, s22, -16
	v_add_u32_e32 v0, s5, v19
	v_add_u32_e32 v12, s14, v18
	v_lshlrev_b64 v[16:17], 12, v[0:1]
	v_lshlrev_b64 v[12:13], 12, v[12:13]
	v_lshl_add_u64 v[16:17], v[10:11], 0, v[16:17]
	v_lshl_add_u64 v[12:13], v[10:11], 0, v[12:13]
	global_load_dword v24, v[16:17], off
	global_load_dword v25, v[12:13], off
	v_mad_u64_u32 v[56:57], s[26:27], v19, s50, v[6:7]
	v_mad_u64_u32 v[58:59], s[26:27], v18, s50, v[6:7]
	s_add_i32 s26, s24, 8
	s_nop 0
	v_or_b32_e32 v19, s26, v2
	v_or_b32_e32 v18, s25, v3
	v_mov_b32_e32 v13, v1
	s_add_i32 s25, s23, 12
	v_add_u32_e32 v0, s5, v19
	v_add_u32_e32 v12, s14, v18
	v_lshlrev_b64 v[16:17], 12, v[0:1]
	v_lshlrev_b64 v[12:13], 12, v[12:13]
	v_lshl_add_u64 v[16:17], v[10:11], 0, v[16:17]
	v_lshl_add_u64 v[12:13], v[10:11], 0, v[12:13]
	global_load_dword v26, v[16:17], off
	global_load_dword v27, v[12:13], off
	v_mad_u64_u32 v[60:61], s[26:27], v19, s50, v[6:7]
	v_mad_u64_u32 v[62:63], s[26:27], v18, s50, v[6:7]
	s_add_i32 s26, s24, 12
	s_nop 0
	v_or_b32_e32 v19, s26, v2
	v_or_b32_e32 v18, s25, v3
	v_mov_b32_e32 v13, v1
	s_add_i32 s25, s23, 16
	v_add_u32_e32 v0, s5, v19
	v_add_u32_e32 v12, s14, v18
	v_lshlrev_b64 v[16:17], 12, v[0:1]
	v_lshlrev_b64 v[12:13], 12, v[12:13]
	v_lshl_add_u64 v[16:17], v[10:11], 0, v[16:17]
	v_lshl_add_u64 v[12:13], v[10:11], 0, v[12:13]
	global_load_dword v28, v[16:17], off
	global_load_dword v29, v[12:13], off
	v_mad_u64_u32 v[64:65], s[26:27], v19, s50, v[6:7]
	v_mad_u64_u32 v[66:67], s[26:27], v18, s50, v[6:7]
	s_add_i32 s26, s24, 16
	s_nop 0
	v_or_b32_e32 v19, s26, v2
	v_or_b32_e32 v18, s25, v3
	v_mov_b32_e32 v13, v1
	s_add_i32 s25, s23, 20
	v_add_u32_e32 v0, s5, v19
	v_add_u32_e32 v12, s14, v18
	v_lshlrev_b64 v[16:17], 12, v[0:1]
	v_lshlrev_b64 v[12:13], 12, v[12:13]
	v_lshl_add_u64 v[16:17], v[10:11], 0, v[16:17]
	v_lshl_add_u64 v[12:13], v[10:11], 0, v[12:13]
	global_load_dword v30, v[16:17], off
	global_load_dword v31, v[12:13], off
	v_mad_u64_u32 v[68:69], s[26:27], v19, s50, v[6:7]
	v_mad_u64_u32 v[70:71], s[26:27], v18, s50, v[6:7]
	s_add_i32 s26, s24, 20
	s_nop 0
	v_or_b32_e32 v19, s26, v2
	v_or_b32_e32 v18, s25, v3
	v_mov_b32_e32 v13, v1
	s_add_i32 s25, s23, 24
	s_add_i32 s23, s23, 28
	v_add_u32_e32 v0, s5, v19
	v_add_u32_e32 v12, s14, v18
	v_lshlrev_b64 v[16:17], 12, v[0:1]
	v_lshlrev_b64 v[12:13], 12, v[12:13]
	v_lshl_add_u64 v[16:17], v[10:11], 0, v[16:17]
	v_lshl_add_u64 v[12:13], v[10:11], 0, v[12:13]
	global_load_dword v32, v[16:17], off
	global_load_dword v33, v[12:13], off
	v_mad_u64_u32 v[72:73], s[26:27], v19, s50, v[6:7]
	v_mad_u64_u32 v[74:75], s[26:27], v18, s50, v[6:7]
	s_add_i32 s26, s24, 24
	s_nop 0
	v_or_b32_e32 v19, s26, v2
	v_or_b32_e32 v18, s25, v3
	v_mov_b32_e32 v13, v1
	s_add_i32 s24, s24, 28
	s_cmp_lg_u32 s22, 0
	v_add_u32_e32 v0, s5, v19
	v_add_u32_e32 v12, s14, v18
	v_lshlrev_b64 v[16:17], 12, v[0:1]
	v_lshlrev_b64 v[12:13], 12, v[12:13]
	v_lshl_add_u64 v[16:17], v[10:11], 0, v[16:17]
	v_lshl_add_u64 v[12:13], v[10:11], 0, v[12:13]
	global_load_dword v34, v[16:17], off
	global_load_dword v35, v[12:13], off
	v_mad_u64_u32 v[76:77], s[26:27], v19, s50, v[6:7]
	v_or_b32_e32 v19, s24, v2
	v_mad_u64_u32 v[78:79], s[26:27], v18, s50, v[6:7]
	v_or_b32_e32 v18, s23, v3
	v_mov_b32_e32 v13, v1
	v_add_u32_e32 v0, s5, v19
	v_add_u32_e32 v12, s14, v18
	v_lshlrev_b64 v[16:17], 12, v[0:1]
	v_lshlrev_b64 v[12:13], 12, v[12:13]
	v_lshl_add_u64 v[16:17], v[10:11], 0, v[16:17]
	v_lshl_add_u64 v[12:13], v[10:11], 0, v[12:13]
	global_load_dword v36, v[16:17], off
	global_load_dword v37, v[12:13], off
	v_mad_u64_u32 v[80:81], s[24:25], v19, s50, v[6:7]
	v_mad_u64_u32 v[82:83], s[24:25], v18, s50, v[6:7]
	s_waitcnt vmcnt(15)
	ds_write_b32 v52, v22
	s_waitcnt vmcnt(14)
	ds_write_b32 v54, v23
	s_waitcnt vmcnt(13)
	ds_write_b32 v56, v24
	s_waitcnt vmcnt(12)
	ds_write_b32 v58, v25
	s_waitcnt vmcnt(11)
	ds_write_b32 v60, v26
	s_waitcnt vmcnt(10)
	ds_write_b32 v62, v27
	s_waitcnt vmcnt(9)
	ds_write_b32 v64, v28
	s_waitcnt vmcnt(8)
	ds_write_b32 v66, v29
	s_waitcnt vmcnt(7)
	ds_write_b32 v68, v30
	s_waitcnt vmcnt(6)
	ds_write_b32 v70, v31
	s_waitcnt vmcnt(5)
	ds_write_b32 v72, v32
	s_waitcnt vmcnt(4)
	ds_write_b32 v74, v33
	s_waitcnt vmcnt(3)
	ds_write_b32 v76, v34
	s_waitcnt vmcnt(2)
	ds_write_b32 v78, v35
	s_waitcnt vmcnt(1)
	ds_write_b32 v80, v36
	s_waitcnt vmcnt(0)
	ds_write_b32 v82, v37
	s_cbranch_scc1 .LBB0_469
; #define LAS __attribute__((address_space(3)))
; __device__ __forceinline__ unsigned pk2(float lo, float hi) { return f2bf(lo) | (f2bf(hi) << 16); }
; __device__ __forceinline__ void transpose_item(const float* W, int K, int N, bf16_t* WT, int k0, int n0, int drow0, LAS float* scr, int lane) {
;     ...
;     const int c = lane & 7;
; #pragma unroll
;     for (int j = 0; j < 4; ++j) { const int n = (lane >> 3) + 8 * j; const LAS float* s = scr + (8 * c) * 33 + n;
;         u32x4 o; o.x = pk2(s[0 * 33], s[1 * 33]); o.y = pk2(s[2 * 33], s[3 * 33]); o.z = pk2(s[4 * 33], s[5 * 33]); o.w = pk2(s[6 * 33], s[7 * 33]);
;         *(u32x4*)(WT + (size_t)(drow0 + n) * K + k0 + 8 * c) = o; }
;     asm volatile("s_waitcnt lgkmcnt(0)" ::: "memory");
	s_lshl_b32 s4, s5, 1
	s_add_u32 s4, s7, s4
	s_waitcnt lgkmcnt(0)
	s_addc_u32 s5, s8, 0
	v_lshlrev_b32_e32 v0, 1, v8
	v_lshl_add_u64 v[10:11], s[4:5], 0, v[0:1]
	ds_read_b32 v0, v7
	ds_read_b32 v12, v7 offset:132
	s_mov_b64 s[4:5], 0xb00000
	v_lshl_add_u64 v[10:11], v[10:11], 0, s[4:5]
	s_waitcnt lgkmcnt(0)
	v_bfe_u32 v13, v0, 16, 1
	v_add3_u32 v0, v0, v13, s44
	v_bfe_u32 v13, v12, 16, 1
	v_lshrrev_b32_e32 v0, 16, v0
	v_add3_u32 v12, v12, v13, s44
	v_and_or_b32 v16, v12, s49, v0
	ds_read_b32 v0, v7 offset:264
	ds_read_b32 v12, v7 offset:396
	s_waitcnt lgkmcnt(1)
	v_bfe_u32 v13, v0, 16, 1
	v_add3_u32 v0, v0, v13, s44
	s_waitcnt lgkmcnt(0)
	v_bfe_u32 v13, v12, 16, 1
	v_lshrrev_b32_e32 v0, 16, v0
	v_add3_u32 v12, v12, v13, s44
	v_and_or_b32 v17, v12, s49, v0
	ds_read_b32 v0, v7 offset:528
	ds_read_b32 v12, v7 offset:660
	s_waitcnt lgkmcnt(1)
	v_bfe_u32 v13, v0, 16, 1
	v_add3_u32 v0, v0, v13, s44
	s_waitcnt lgkmcnt(0)
	v_bfe_u32 v13, v12, 16, 1
	v_lshrrev_b32_e32 v0, 16, v0
	v_add3_u32 v12, v12, v13, s44
	v_and_or_b32 v18, v12, s49, v0
	ds_read_b32 v0, v7 offset:792
	ds_read_b32 v12, v7 offset:924
	s_waitcnt lgkmcnt(1)
	v_bfe_u32 v13, v0, 16, 1
	v_add3_u32 v0, v0, v13, s44
	s_waitcnt lgkmcnt(0)
	v_bfe_u32 v13, v12, 16, 1
	v_lshrrev_b32_e32 v0, 16, v0
	v_add3_u32 v12, v12, v13, s44
	v_and_or_b32 v19, v12, s49, v0
	v_or_b32_e32 v0, s1, v5
	v_mul_u32_u24_e32 v0, 0xb00, v0
	v_lshlrev_b32_e32 v0, 1, v0
	v_lshl_add_u64 v[12:13], v[10:11], 0, v[0:1]
	flat_store_dwordx4 v[12:13], v[16:19]
	ds_read_b32 v0, v7 offset:32
	ds_read_b32 v12, v7 offset:164
	s_waitcnt lgkmcnt(0)
	v_bfe_u32 v13, v0, 16, 1
	v_add3_u32 v0, v0, v13, s44
	v_bfe_u32 v13, v12, 16, 1
	v_lshrrev_b32_e32 v0, 16, v0
	v_add3_u32 v12, v12, v13, s44
	v_and_or_b32 v16, v12, s49, v0
	ds_read_b32 v0, v7 offset:296
	ds_read_b32 v12, v7 offset:428
	s_waitcnt lgkmcnt(0)
	v_bfe_u32 v13, v0, 16, 1
	v_add3_u32 v0, v0, v13, s44
	v_bfe_u32 v13, v12, 16, 1
	v_lshrrev_b32_e32 v0, 16, v0
	v_add3_u32 v12, v12, v13, s44
	v_and_or_b32 v17, v12, s49, v0
	ds_read_b32 v0, v7 offset:560
	ds_read_b32 v12, v7 offset:692
	s_waitcnt lgkmcnt(0)
	v_bfe_u32 v13, v0, 16, 1
	v_add3_u32 v0, v0, v13, s44
	v_bfe_u32 v13, v12, 16, 1
	v_lshrrev_b32_e32 v0, 16, v0
	v_add3_u32 v12, v12, v13, s44
	v_and_or_b32 v18, v12, s49, v0
	ds_read_b32 v0, v7 offset:824
	ds_read_b32 v12, v7 offset:956
	s_waitcnt lgkmcnt(0)
	v_bfe_u32 v13, v0, 16, 1
	v_add3_u32 v0, v0, v13, s44
	v_bfe_u32 v13, v12, 16, 1
	v_lshrrev_b32_e32 v0, 16, v0
	v_add3_u32 v12, v12, v13, s44
	v_and_or_b32 v19, v12, s49, v0
	v_or_b32_e32 v0, s1, v9
	v_mul_u32_u24_e32 v0, 0xb00, v0
	v_lshlrev_b32_e32 v0, 1, v0
	v_lshl_add_u64 v[12:13], v[10:11], 0, v[0:1]
	flat_store_dwordx4 v[12:13], v[16:19]
	ds_read_b32 v0, v7 offset:64
	ds_read_b32 v12, v7 offset:196
	s_waitcnt lgkmcnt(0)
	v_bfe_u32 v13, v0, 16, 1
	v_add3_u32 v0, v0, v13, s44
	v_bfe_u32 v13, v12, 16, 1
	v_lshrrev_b32_e32 v0, 16, v0
	v_add3_u32 v12, v12, v13, s44
	v_and_or_b32 v16, v12, s49, v0
	ds_read_b32 v0, v7 offset:328
	ds_read_b32 v12, v7 offset:460
	s_waitcnt lgkmcnt(0)
	v_bfe_u32 v13, v0, 16, 1
	v_add3_u32 v0, v0, v13, s44
	v_bfe_u32 v13, v12, 16, 1
	v_lshrrev_b32_e32 v0, 16, v0
	v_add3_u32 v12, v12, v13, s44
	v_and_or_b32 v17, v12, s49, v0
	ds_read_b32 v0, v7 offset:592
	ds_read_b32 v12, v7 offset:724
	s_waitcnt lgkmcnt(0)
	v_bfe_u32 v13, v0, 16, 1
	v_add3_u32 v0, v0, v13, s44
	v_bfe_u32 v13, v12, 16, 1
	v_lshrrev_b32_e32 v0, 16, v0
	v_add3_u32 v12, v12, v13, s44
	v_and_or_b32 v18, v12, s49, v0
	ds_read_b32 v0, v7 offset:856
	ds_read_b32 v12, v7 offset:988
	s_waitcnt lgkmcnt(0)
	v_bfe_u32 v13, v0, 16, 1
	v_add3_u32 v0, v0, v13, s44
	v_bfe_u32 v13, v12, 16, 1
	v_lshrrev_b32_e32 v0, 16, v0
	v_add3_u32 v12, v12, v13, s44
	v_and_or_b32 v19, v12, s49, v0
	v_or_b32_e32 v0, s1, v14
	v_mul_u32_u24_e32 v0, 0xb00, v0
	v_lshlrev_b32_e32 v0, 1, v0
	v_lshl_add_u64 v[12:13], v[10:11], 0, v[0:1]
	flat_store_dwordx4 v[12:13], v[16:19]
	ds_read_b32 v0, v7 offset:96
	ds_read_b32 v12, v7 offset:228
	s_waitcnt lgkmcnt(0)
	v_bfe_u32 v13, v0, 16, 1
	v_add3_u32 v0, v0, v13, s44
	v_bfe_u32 v13, v12, 16, 1
	v_lshrrev_b32_e32 v0, 16, v0
	v_add3_u32 v12, v12, v13, s44
	v_and_or_b32 v16, v12, s49, v0
	ds_read_b32 v0, v7 offset:360
	ds_read_b32 v12, v7 offset:492
	s_waitcnt lgkmcnt(0)
	v_bfe_u32 v13, v0, 16, 1
	v_add3_u32 v0, v0, v13, s44
	v_bfe_u32 v13, v12, 16, 1
	v_lshrrev_b32_e32 v0, 16, v0
	v_add3_u32 v12, v12, v13, s44
	v_and_or_b32 v17, v12, s49, v0
	ds_read_b32 v0, v7 offset:624
	ds_read_b32 v12, v7 offset:756
	s_waitcnt lgkmcnt(0)
	v_bfe_u32 v13, v0, 16, 1
	v_add3_u32 v0, v0, v13, s44
	v_bfe_u32 v13, v12, 16, 1
	v_lshrrev_b32_e32 v0, 16, v0
	v_add3_u32 v12, v12, v13, s44
	v_and_or_b32 v18, v12, s49, v0
	ds_read_b32 v0, v7 offset:888
	ds_read_b32 v12, v7 offset:1020
	s_waitcnt lgkmcnt(0)
	v_bfe_u32 v13, v0, 16, 1
	v_add3_u32 v0, v0, v13, s44
	v_bfe_u32 v13, v12, 16, 1
	v_lshrrev_b32_e32 v0, 16, v0
	v_add3_u32 v12, v12, v13, s44
	v_and_or_b32 v19, v12, s49, v0
	v_or_b32_e32 v0, s1, v15
	v_mul_u32_u24_e32 v0, 0xb00, v0
	v_lshlrev_b32_e32 v0, 1, v0
	v_lshl_add_u64 v[10:11], v[10:11], 0, v[0:1]
	flat_store_dwordx4 v[10:11], v[16:19]
	s_waitcnt lgkmcnt(0)

; __device__ __forceinline__ void transpose_item(const float* W, int K, int N, bf16_t* WT, int k0, int n0, int drow0, LAS float* scr, int lane) {
;     ...
;     for (int i = 0; i < 32; ++i) { const int kk = 2 * i + (lane >> 5); scr[kk * 33 + (lane & 31)] = W[(size_t)(k0 + kk) * N + n0 + (lane & 31)]; }
;     asm volatile("s_waitcnt lgkmcnt(0)" ::: "memory");
.LBB0_473:
	s_lshl_b32 s23, s14, 1
	s_lshl_b32 s22, s9, 1
	v_or_b32_e32 v18, s23, v2
	v_or_b32_e32 v0, s22, v3
	v_add_u32_e32 v12, s0, v18
	v_add_u32_e32 v16, s5, v0
	v_mad_i64_i32 v[12:13], s[24:25], v12, s43, v[10:11]
	v_mad_i64_i32 v[16:17], s[24:25], v16, s43, v[10:11]
	global_load_dword v22, v[12:13], off
	global_load_dword v23, v[16:17], off
	v_mad_u64_u32 v[52:53], s[24:25], v18, s50, v[6:7]
	v_mad_u64_u32 v[54:55], s[24:25], v0, s50, v[6:7]
	s_add_i32 s25, s23, 4
	s_add_i32 s24, s22, 4
	v_or_b32_e32 v18, s25, v2
	v_or_b32_e32 v0, s24, v3
	s_add_i32 s14, s14, 16
	s_add_i32 s9, s9, 16
	s_add_i32 s15, s15, -16
	v_add_u32_e32 v12, s0, v18
	v_add_u32_e32 v16, s5, v0
	v_mad_i64_i32 v[12:13], s[24:25], v12, s43, v[10:11]
	v_mad_i64_i32 v[16:17], s[24:25], v16, s43, v[10:11]
	global_load_dword v24, v[12:13], off
	global_load_dword v25, v[16:17], off
	v_mad_u64_u32 v[56:57], s[24:25], v18, s50, v[6:7]
	v_mad_u64_u32 v[58:59], s[24:25], v0, s50, v[6:7]
	s_add_i32 s25, s23, 8
	s_add_i32 s24, s22, 8
	v_or_b32_e32 v18, s25, v2
	v_or_b32_e32 v0, s24, v3
	v_add_u32_e32 v12, s0, v18
	v_add_u32_e32 v16, s5, v0
	v_mad_i64_i32 v[12:13], s[24:25], v12, s43, v[10:11]
	v_mad_i64_i32 v[16:17], s[24:25], v16, s43, v[10:11]
	global_load_dword v26, v[12:13], off
	global_load_dword v27, v[16:17], off
	v_mad_u64_u32 v[60:61], s[24:25], v18, s50, v[6:7]
	v_mad_u64_u32 v[62:63], s[24:25], v0, s50, v[6:7]
	s_add_i32 s25, s23, 12
	s_add_i32 s24, s22, 12
	v_or_b32_e32 v18, s25, v2
	v_or_b32_e32 v0, s24, v3
	v_add_u32_e32 v12, s0, v18
	v_add_u32_e32 v16, s5, v0
	v_mad_i64_i32 v[12:13], s[24:25], v12, s43, v[10:11]
	v_mad_i64_i32 v[16:17], s[24:25], v16, s43, v[10:11]
	global_load_dword v28, v[12:13], off
	global_load_dword v29, v[16:17], off
	v_mad_u64_u32 v[64:65], s[24:25], v18, s50, v[6:7]
	v_mad_u64_u32 v[66:67], s[24:25], v0, s50, v[6:7]
	s_add_i32 s25, s23, 16
	s_add_i32 s24, s22, 16
	v_or_b32_e32 v18, s25, v2
	v_or_b32_e32 v0, s24, v3
	v_add_u32_e32 v12, s0, v18
	v_add_u32_e32 v16, s5, v0
	v_mad_i64_i32 v[12:13], s[24:25], v12, s43, v[10:11]
	v_mad_i64_i32 v[16:17], s[24:25], v16, s43, v[10:11]
	global_load_dword v30, v[12:13], off
	global_load_dword v31, v[16:17], off
	v_mad_u64_u32 v[68:69], s[24:25], v18, s50, v[6:7]
	v_mad_u64_u32 v[70:71], s[24:25], v0, s50, v[6:7]
	s_add_i32 s25, s23, 20
	s_add_i32 s24, s22, 20
	v_or_b32_e32 v18, s25, v2
	v_or_b32_e32 v0, s24, v3
	v_add_u32_e32 v12, s0, v18
	v_add_u32_e32 v16, s5, v0
	v_mad_i64_i32 v[12:13], s[24:25], v12, s43, v[10:11]
	v_mad_i64_i32 v[16:17], s[24:25], v16, s43, v[10:11]
	global_load_dword v32, v[12:13], off
	global_load_dword v33, v[16:17], off
	v_mad_u64_u32 v[72:73], s[24:25], v18, s50, v[6:7]
	v_mad_u64_u32 v[74:75], s[24:25], v0, s50, v[6:7]
	s_add_i32 s25, s23, 24
	s_add_i32 s24, s22, 24
	v_or_b32_e32 v18, s25, v2
	v_or_b32_e32 v0, s24, v3
	s_add_i32 s23, s23, 28
	s_add_i32 s22, s22, 28
	s_cmp_lg_u32 s15, 0
	v_add_u32_e32 v12, s0, v18
	v_add_u32_e32 v16, s5, v0
	v_mad_i64_i32 v[12:13], s[24:25], v12, s43, v[10:11]
	v_mad_i64_i32 v[16:17], s[24:25], v16, s43, v[10:11]
	global_load_dword v34, v[12:13], off
	global_load_dword v35, v[16:17], off
	v_mad_u64_u32 v[76:77], s[24:25], v18, s50, v[6:7]
	v_or_b32_e32 v18, s23, v2
	v_mad_u64_u32 v[78:79], s[24:25], v0, s50, v[6:7]
	v_or_b32_e32 v0, s22, v3
	v_add_u32_e32 v12, s0, v18
	v_add_u32_e32 v16, s5, v0
	v_mad_i64_i32 v[12:13], s[22:23], v12, s43, v[10:11]
	v_mad_i64_i32 v[16:17], s[22:23], v16, s43, v[10:11]
	global_load_dword v36, v[12:13], off
	global_load_dword v37, v[16:17], off
	v_mad_u64_u32 v[80:81], s[22:23], v18, s50, v[6:7]
	v_mad_u64_u32 v[82:83], s[22:23], v0, s50, v[6:7]
	s_waitcnt vmcnt(15)
	ds_write_b32 v52, v22
	s_waitcnt vmcnt(14)
	ds_write_b32 v54, v23
	s_waitcnt vmcnt(13)
	ds_write_b32 v56, v24
	s_waitcnt vmcnt(12)
	ds_write_b32 v58, v25
	s_waitcnt vmcnt(11)
	ds_write_b32 v60, v26
	s_waitcnt vmcnt(10)
	ds_write_b32 v62, v27
	s_waitcnt vmcnt(9)
	ds_write_b32 v64, v28
	s_waitcnt vmcnt(8)
	ds_write_b32 v66, v29
	s_waitcnt vmcnt(7)
	ds_write_b32 v68, v30
	s_waitcnt vmcnt(6)
	ds_write_b32 v70, v31
	s_waitcnt vmcnt(5)
	ds_write_b32 v72, v32
	s_waitcnt vmcnt(4)
	ds_write_b32 v74, v33
	s_waitcnt vmcnt(3)
	ds_write_b32 v76, v34
	s_waitcnt vmcnt(2)
	ds_write_b32 v78, v35
	s_waitcnt vmcnt(1)
	ds_write_b32 v80, v36
	s_waitcnt vmcnt(0)
	ds_write_b32 v82, v37
	s_cbranch_scc1 .LBB0_473
; #define LAS __attribute__((address_space(3)))
; __device__ __forceinline__ unsigned pk2(float lo, float hi) { return f2bf(lo) | (f2bf(hi) << 16); }
; __device__ __forceinline__ void transpose_item(const float* W, int K, int N, bf16_t* WT, int k0, int n0, int drow0, LAS float* scr, int lane) {
;     ...
;     const int c = lane & 7;
; #pragma unroll
;     for (int j = 0; j < 4; ++j) { const int n = (lane >> 3) + 8 * j; const LAS float* s = scr + (8 * c) * 33 + n;
;         u32x4 o; o.x = pk2(s[0 * 33], s[1 * 33]); o.y = pk2(s[2 * 33], s[3 * 33]); o.z = pk2(s[4 * 33], s[5 * 33]); o.w = pk2(s[6 * 33], s[7 * 33]);
;         *(u32x4*)(WT + (size_t)(drow0 + n) * K + k0 + 8 * c) = o; }
;     asm volatile("s_waitcnt lgkmcnt(0)" ::: "memory");
; template <bool GU> __device__ __forceinline__ void transpose_matrix_item(const float* W, int K, int N, bf16_t* WT, int item, LAS float* scr, int lane) {
;     const int nblk = N / 32, kb = item / nblk, nb = item % nblk, n0 = 32 * nb;
;     int drow0 = n0;
;     if (GU) { const int isu = n0 >= DFF ? 1 : 0, ff0 = n0 - isu * DFF; drow0 = 256 * (ff0 >> 7) + 128 * isu + (ff0 & 127); }
	s_cmpk_gt_i32 s1, 0x57
	s_cselect_b32 s1, 0xfffff500, 0
	s_cselect_b32 s5, 0x80, 0
	s_add_i32 s1, s1, s4
	s_lshl_b32 s1, s1, 1
	s_and_b32 s4, s4, 0x60
	s_and_b32 s1, s1, 0xffffff00
	s_or_b32 s4, s4, s5
	s_or_b32 s4, s4, s1
	s_ashr_i32 s1, s0, 31
	s_lshl_b64 s[0:1], s[0:1], 1
	s_add_u32 s0, s7, s0
	s_waitcnt lgkmcnt(0)
	s_addc_u32 s1, s8, s1
	v_lshlrev_b32_e32 v0, 1, v8
	v_lshl_add_u64 v[10:11], s[0:1], 0, v[0:1]
	ds_read_b32 v0, v7
	ds_read_b32 v12, v7 offset:132
	s_waitcnt lgkmcnt(0)
	v_bfe_u32 v13, v0, 16, 1
	v_add3_u32 v0, v0, v13, s44
	v_bfe_u32 v13, v12, 16, 1
	v_lshrrev_b32_e32 v0, 16, v0
	v_add3_u32 v12, v12, v13, s44
	v_and_or_b32 v16, v12, s49, v0
	ds_read_b32 v0, v7 offset:264
	ds_read_b32 v12, v7 offset:396
	s_waitcnt lgkmcnt(1)
	v_bfe_u32 v13, v0, 16, 1
	v_add3_u32 v0, v0, v13, s44
	s_waitcnt lgkmcnt(0)
	v_bfe_u32 v13, v12, 16, 1
	v_lshrrev_b32_e32 v0, 16, v0
	v_add3_u32 v12, v12, v13, s44
	v_and_or_b32 v17, v12, s49, v0
	ds_read_b32 v0, v7 offset:528
	ds_read_b32 v12, v7 offset:660
	s_waitcnt lgkmcnt(1)
	v_bfe_u32 v13, v0, 16, 1
	v_add3_u32 v0, v0, v13, s44
	s_waitcnt lgkmcnt(0)
	v_bfe_u32 v13, v12, 16, 1
	v_lshrrev_b32_e32 v0, 16, v0
	v_add3_u32 v12, v12, v13, s44
	v_and_or_b32 v18, v12, s49, v0
	ds_read_b32 v0, v7 offset:792
	ds_read_b32 v12, v7 offset:924
	s_waitcnt lgkmcnt(1)
	v_bfe_u32 v13, v0, 16, 1
	v_add3_u32 v0, v0, v13, s44
	s_waitcnt lgkmcnt(0)
	v_bfe_u32 v13, v12, 16, 1
	v_lshrrev_b32_e32 v0, 16, v0
	v_add3_u32 v12, v12, v13, s44
	v_and_or_b32 v19, v12, s49, v0
	v_or_b32_e32 v12, s4, v5
	v_ashrrev_i32_e32 v13, 31, v12
	v_lshlrev_b64 v[12:13], 11, v[12:13]
	v_lshl_add_u64 v[12:13], v[10:11], 0, v[12:13]
	flat_store_dwordx4 v[12:13], v[16:19]
	ds_read_b32 v0, v7 offset:32
	ds_read_b32 v12, v7 offset:164
	s_waitcnt lgkmcnt(0)
	v_bfe_u32 v13, v0, 16, 1
	v_add3_u32 v0, v0, v13, s44
	v_bfe_u32 v13, v12, 16, 1
	v_lshrrev_b32_e32 v0, 16, v0
	v_add3_u32 v12, v12, v13, s44
	v_and_or_b32 v16, v12, s49, v0
	ds_read_b32 v0, v7 offset:296
	ds_read_b32 v12, v7 offset:428
	s_waitcnt lgkmcnt(0)
	v_bfe_u32 v13, v0, 16, 1
	v_add3_u32 v0, v0, v13, s44
	v_bfe_u32 v13, v12, 16, 1
	v_lshrrev_b32_e32 v0, 16, v0
	v_add3_u32 v12, v12, v13, s44
	v_and_or_b32 v17, v12, s49, v0
	ds_read_b32 v0, v7 offset:560
	ds_read_b32 v12, v7 offset:692
	s_waitcnt lgkmcnt(0)
	v_bfe_u32 v13, v0, 16, 1
	v_add3_u32 v0, v0, v13, s44
	v_bfe_u32 v13, v12, 16, 1
	v_lshrrev_b32_e32 v0, 16, v0
	v_add3_u32 v12, v12, v13, s44
	v_and_or_b32 v18, v12, s49, v0
	ds_read_b32 v0, v7 offset:824
	ds_read_b32 v12, v7 offset:956
	s_waitcnt lgkmcnt(0)
	v_bfe_u32 v13, v0, 16, 1
	v_add3_u32 v0, v0, v13, s44
	v_bfe_u32 v13, v12, 16, 1
	v_lshrrev_b32_e32 v0, 16, v0
	v_add3_u32 v12, v12, v13, s44
	v_and_or_b32 v19, v12, s49, v0
	v_or_b32_e32 v12, s4, v9
	v_ashrrev_i32_e32 v13, 31, v12
	v_lshlrev_b64 v[12:13], 11, v[12:13]
	v_lshl_add_u64 v[12:13], v[10:11], 0, v[12:13]
	flat_store_dwordx4 v[12:13], v[16:19]
	ds_read_b32 v0, v7 offset:64
	ds_read_b32 v12, v7 offset:196
	s_waitcnt lgkmcnt(0)
	v_bfe_u32 v13, v0, 16, 1
	v_add3_u32 v0, v0, v13, s44
	v_bfe_u32 v13, v12, 16, 1
	v_lshrrev_b32_e32 v0, 16, v0
	v_add3_u32 v12, v12, v13, s44
	v_and_or_b32 v16, v12, s49, v0
	ds_read_b32 v0, v7 offset:328
	ds_read_b32 v12, v7 offset:460
	s_waitcnt lgkmcnt(0)
	v_bfe_u32 v13, v0, 16, 1
	v_add3_u32 v0, v0, v13, s44
	v_bfe_u32 v13, v12, 16, 1
	v_lshrrev_b32_e32 v0, 16, v0
	v_add3_u32 v12, v12, v13, s44
	v_and_or_b32 v17, v12, s49, v0
	ds_read_b32 v0, v7 offset:592
	ds_read_b32 v12, v7 offset:724
	s_waitcnt lgkmcnt(0)
	v_bfe_u32 v13, v0, 16, 1
	v_add3_u32 v0, v0, v13, s44
	v_bfe_u32 v13, v12, 16, 1
	v_lshrrev_b32_e32 v0, 16, v0
	v_add3_u32 v12, v12, v13, s44
	v_and_or_b32 v18, v12, s49, v0
	ds_read_b32 v0, v7 offset:856
	ds_read_b32 v12, v7 offset:988
	s_waitcnt lgkmcnt(0)
	v_bfe_u32 v13, v0, 16, 1
	v_add3_u32 v0, v0, v13, s44
	v_bfe_u32 v13, v12, 16, 1
	v_lshrrev_b32_e32 v0, 16, v0
	v_add3_u32 v12, v12, v13, s44
	v_and_or_b32 v19, v12, s49, v0
	v_or_b32_e32 v12, s4, v14
	v_ashrrev_i32_e32 v13, 31, v12
	v_lshlrev_b64 v[12:13], 11, v[12:13]
	v_lshl_add_u64 v[12:13], v[10:11], 0, v[12:13]
	flat_store_dwordx4 v[12:13], v[16:19]
	ds_read_b32 v0, v7 offset:96
	ds_read_b32 v12, v7 offset:228
	s_waitcnt lgkmcnt(0)
	v_bfe_u32 v13, v0, 16, 1
	v_add3_u32 v0, v0, v13, s44
	v_bfe_u32 v13, v12, 16, 1
	v_lshrrev_b32_e32 v0, 16, v0
	v_add3_u32 v12, v12, v13, s44
	v_and_or_b32 v16, v12, s49, v0
	ds_read_b32 v0, v7 offset:360
	ds_read_b32 v12, v7 offset:492
	s_waitcnt lgkmcnt(0)
	v_bfe_u32 v13, v0, 16, 1
	v_add3_u32 v0, v0, v13, s44
	v_bfe_u32 v13, v12, 16, 1
	v_lshrrev_b32_e32 v0, 16, v0
	v_add3_u32 v12, v12, v13, s44
	v_and_or_b32 v17, v12, s49, v0
	ds_read_b32 v0, v7 offset:624
	ds_read_b32 v12, v7 offset:756
	s_waitcnt lgkmcnt(0)
	v_bfe_u32 v13, v0, 16, 1
	v_add3_u32 v0, v0, v13, s44
	v_bfe_u32 v13, v12, 16, 1
	v_lshrrev_b32_e32 v0, 16, v0
	v_add3_u32 v12, v12, v13, s44
	v_and_or_b32 v18, v12, s49, v0
	ds_read_b32 v0, v7 offset:888
	ds_read_b32 v12, v7 offset:1020
	s_waitcnt lgkmcnt(0)
	v_bfe_u32 v13, v0, 16, 1
	v_add3_u32 v0, v0, v13, s44
	v_bfe_u32 v13, v12, 16, 1
	v_lshrrev_b32_e32 v0, 16, v0
	v_add3_u32 v12, v12, v13, s44
	v_and_or_b32 v19, v12, s49, v0
	v_or_b32_e32 v12, s4, v15
	v_ashrrev_i32_e32 v13, 31, v12
	v_lshlrev_b64 v[12:13], 11, v[12:13]
	v_lshl_add_u64 v[10:11], v[10:11], 0, v[12:13]
	flat_store_dwordx4 v[10:11], v[16:19]
	s_waitcnt lgkmcnt(0)
	s_branch .LBB0_430
